# residual-add GEMM epilogue pipelined (batched loads, counted vmcnt); norm phases: gain vector hoisted out of row loop, sample-row split-K partial sums fetched 18 loads at a time; GLA LDS stores moved
# speedup vs baseline: 1.1734x; 1.0496x over previous
; __device__ __forceinline__ unsigned pk2(float lo, float hi) { unsigned r; asm("v_cvt_pk_bf16_f32 %0, %1, %2" : "=v"(r) : "v"(lo), "v"(hi)); return r; }
; __device__ __forceinline__ void phase_norm(const Params& p, unsigned char* sm, int mode, const int TIDX, const int BIDX) {
;     const int tid = TIDX, wid = tid >> 6, lane = tid & 63, wgid = BIDX * 8 + wid, nw = gridDim.x * 8;
;     float* X = p.out;
;     const float* g = mode == 0 ? p.in[12] : (mode == 1 ? p.in[26] : p.in[29]);
;     for (int r = wgid; r < TT; r += nw) {
;         f32x4 v[8]; float s = 0.f;
;         load_row(p, r, mode, lane, v);
; #pragma unroll
;         for (int j = 0; j < 8; ++j) s += v[j][0] * v[j][0] + v[j][1] * v[j][1] + v[j][2] * v[j][2] + v[j][3] * v[j][3];
;         s = wave_sum(s); const float rs = rsqrtf(s * (1.0f / DM) + EPS);
;         if (mode < 2) {
;             bf16_t* o = (bf16_t*)(p.ws + WS_ABUF) + (size_t)r * DM;
; #pragma unroll
;             for (int j = 0; j < 8; ++j) { const f32x4 gg = ((const f32x4*)g)[j * 64 + lane]; u32x2 w; w.x = pk2(v[j][0] * rs * gg[0], v[j][1] * rs * gg[1]); w.y = pk2(v[j][2] * rs * gg[2], v[j][3] * rs * gg[3]); ((u32x2*)o)[j * 64 + lane] = w; }
;         } else {
; #pragma unroll
;             for (int j = 0; j < 8; ++j) { const f32x4 gg = ((const f32x4*)g)[j * 64 + lane]; ((f32x4*)(X + (size_t)r * DM))[j * 64 + lane] = v[j] * rs * gg; }
; __global__ __launch_bounds__(512, 2) void mega(Params p_unused, int ph_lo_unused, int ph_hi_unused, int rep_unused, int pad_unused) {
;     ...
;         Params p;
; #pragma unroll
;         for (int i = 0; i < 30; ++i) p.in[i] = ka->p.in[i];
;         p.out = ka->p.out; p.ws = ka->p.ws;
;         const bool is_gemm = (ph == 1 || ph == 2 || ph == 4 || ph == 7 || ph == 9 || ph == 10);
.LBB0_11:
	v_readlane_b32 s68, v254, 1
	v_readlane_b32 s69, v254, 2
	v_readlane_b32 s0, v254, 3
	s_mov_b64 s[70:71], 0
	s_cmp_lt_i32 s48, 6
	v_lshl_or_b32 v199, s0, 6, v169
	v_readlane_b32 s0, v254, 0
	s_load_dwordx16 s[8:23], s[68:69], 0x0
	s_load_dwordx2 s[4:5], s[68:69], 0xb0
	v_writelane_b32 v254, s0, 41
	s_waitcnt lgkmcnt(0)
	v_writelane_b32 v254, s8, 42
	s_nop 1
	v_writelane_b32 v254, s9, 43
	v_writelane_b32 v254, s10, 44
	v_writelane_b32 v254, s11, 45
	v_writelane_b32 v254, s12, 46
	v_writelane_b32 v254, s13, 47
	v_writelane_b32 v254, s14, 48
	v_writelane_b32 v254, s15, 49
	v_writelane_b32 v254, s16, 50
	v_writelane_b32 v254, s17, 51
	v_writelane_b32 v254, s18, 52
	v_writelane_b32 v254, s19, 53
	v_writelane_b32 v254, s20, 54
	v_writelane_b32 v254, s21, 55
	v_writelane_b32 v254, s22, 56
	v_writelane_b32 v254, s23, 57
	s_load_dwordx16 s[8:23], s[68:69], 0x40
	s_waitcnt lgkmcnt(0)
	v_writelane_b32 v254, s8, 58
	s_nop 1
	v_writelane_b32 v255, s14, 0
	v_writelane_b32 v255, s15, 1
	v_writelane_b32 v255, s16, 2
	v_writelane_b32 v255, s17, 3
	v_writelane_b32 v255, s18, 4
	v_writelane_b32 v254, s9, 59
	v_writelane_b32 v255, s19, 5
	v_writelane_b32 v254, s10, 60
	v_writelane_b32 v255, s20, 6
	v_writelane_b32 v254, s11, 61
	v_writelane_b32 v255, s21, 7
	v_writelane_b32 v254, s12, 62
	v_writelane_b32 v255, s22, 8
	v_writelane_b32 v254, s13, 63
	v_writelane_b32 v255, s23, 9
	s_load_dwordx8 s[8:15], s[68:69], 0x90
	v_writelane_b32 v255, s4, 10
	s_load_dwordx16 s[16:31], s[68:69], 0xc0
	s_nop 0
	v_writelane_b32 v255, s5, 11
	s_waitcnt lgkmcnt(0)
	v_writelane_b32 v255, s8, 12
	s_mov_b64 s[4:5], 0
	s_nop 0
	v_writelane_b32 v255, s9, 13
	v_writelane_b32 v255, s10, 14
	v_writelane_b32 v255, s11, 15
	v_writelane_b32 v255, s12, 16
	v_writelane_b32 v255, s13, 17
	v_writelane_b32 v255, s14, 18
	v_writelane_b32 v255, s15, 19
	v_writelane_b32 v255, s16, 20
	s_mov_b64 s[8:9], -1
	s_nop 0
	v_writelane_b32 v255, s17, 21
	v_writelane_b32 v255, s18, 22
	v_writelane_b32 v255, s19, 23
	v_writelane_b32 v255, s20, 24
	v_writelane_b32 v255, s21, 25
	v_writelane_b32 v255, s22, 26
	v_writelane_b32 v255, s23, 27
	v_writelane_b32 v255, s24, 28
	v_writelane_b32 v255, s25, 29
	v_writelane_b32 v255, s26, 30
	v_writelane_b32 v255, s27, 31
	v_writelane_b32 v255, s28, 32
	v_writelane_b32 v255, s29, 33
	v_writelane_b32 v255, s30, 34
	v_writelane_b32 v255, s31, 35
	s_cbranch_scc1 .LBB0_192
	s_cmp_gt_i32 s48, 7
	s_cbranch_scc0 .LBB0_36
	s_cmp_gt_i32 s48, 8
	s_cbranch_scc0 .LBB0_26
	s_cmp_gt_i32 s48, 10
	s_mov_b64 s[4:5], -1
	s_cbranch_scc0 .LBB0_25
	s_cmp_eq_u32 s48, 11
	s_cbranch_scc0 .LBB0_24
	v_readlane_b32 s0, v254, 41
	v_ashrrev_i32_e32 v2, 6, v199
	s_lshl_b32 s12, s0, 3
	v_add_u32_e32 v34, s12, v2
	s_movk_i32 s0, 0x4200
	v_cmp_gt_i32_e32 vcc, s0, v34
	s_and_saveexec_b64 s[4:5], vcc
	s_cbranch_execz .LBB0_23
	v_readlane_b32 s8, v254, 4
	v_readlane_b32 s9, v254, 5
	s_load_dword s0, s[8:9], 0x0
	v_cmp_lt_i32_e32 vcc, v189, v188
	v_and_b32_e32 v36, 63, v199
	v_or_b32_e32 v4, 0x100, v36
	v_cndmask_b32_e32 v0, v169, v189, vcc
	v_cmp_lt_i32_e32 vcc, v190, v188
	v_lshlrev_b32_e32 v37, 2, v0
	v_or_b32_e32 v6, 0x140, v36
	v_cndmask_b32_e32 v0, v169, v190, vcc
	v_cmp_lt_i32_e32 vcc, v191, v188
	v_lshlrev_b32_e32 v66, 2, v0
	s_waitcnt lgkmcnt(0)
	s_lshl_b32 s8, s0, 3
	v_cndmask_b32_e32 v0, v169, v191, vcc
	v_cmp_lt_i32_e32 vcc, v192, v188
	v_lshlrev_b32_e32 v67, 2, v0
	v_lshlrev_b32_e32 v12, 4, v4
	v_cndmask_b32_e32 v0, v169, v192, vcc
	v_cmp_lt_i32_e32 vcc, v193, v188
	v_mov_b32_e32 v13, v1
	v_or_b32_e32 v8, 0x180, v36
	v_lshlrev_b32_e32 v68, 2, v0
	v_cndmask_b32_e32 v0, v169, v193, vcc
	v_cmp_lt_i32_e32 vcc, v194, v188
	v_lshl_add_u64 v[40:41], s[26:27], 0, v[12:13]
	v_lshlrev_b32_e32 v12, 4, v6
	s_add_u32 s10, s30, 0x1afe4000
	v_or_b32_e32 v10, 0x1c0, v36
	v_lshlrev_b32_e32 v69, 2, v0
	v_cndmask_b32_e32 v0, v169, v194, vcc
	v_lshl_add_u64 v[42:43], s[26:27], 0, v[12:13]
	v_lshlrev_b32_e32 v12, 4, v8
	s_addc_u32 s11, s31, 0
	v_ashrrev_i32_e32 v3, 31, v2
	s_ashr_i32 s13, s12, 31
	v_lshlrev_b32_e32 v70, 2, v0
	v_lshlrev_b32_e32 v0, 4, v36
	v_lshl_add_u64 v[44:45], s[26:27], 0, v[12:13]
	v_lshlrev_b32_e32 v12, 4, v10
	v_lshl_add_u64 v[2:3], v[2:3], 0, s[12:13]
	s_ashr_i32 s9, s8, 31
	v_lshl_add_u64 v[38:39], s[26:27], 0, v[0:1]
	v_lshl_add_u64 v[46:47], s[26:27], 0, v[12:13]
	v_lshl_add_u64 v[48:49], s[28:29], 0, v[0:1]
	v_lshlrev_b64 v[50:51], 13, v[2:3]
	s_lshl_b64 s[12:13], s[8:9], 13
	s_mov_b64 s[14:15], 0
	v_lshlrev_b32_e32 v52, 4, v4
	v_lshlrev_b32_e32 v54, 4, v6
	v_lshlrev_b32_e32 v56, 4, v8
	v_lshlrev_b32_e32 v58, 4, v10
	global_load_dwordx4 v[204:207], v[38:39], off
	global_load_dwordx4 v[208:211], v[38:39], off offset:1024
	global_load_dwordx4 v[212:215], v[38:39], off offset:2048
	global_load_dwordx4 v[216:219], v[38:39], off offset:3072
	global_load_dwordx4 v[220:223], v[40:41], off
	global_load_dwordx4 v[224:227], v[42:43], off
	global_load_dwordx4 v[228:231], v[44:45], off
	global_load_dwordx4 v[232:235], v[46:47], off
	s_waitcnt vmcnt(0)
	s_branch .LBB0_19
; __device__ __forceinline__ unsigned pk2(float lo, float hi) { unsigned r; asm("v_cvt_pk_bf16_f32 %0, %1, %2" : "=v"(r) : "v"(lo), "v"(hi)); return r; }
; __device__ __forceinline__ void phase_norm(const Params& p, unsigned char* sm, int mode, const int TIDX, const int BIDX) {
;     ...
;     for (int r = wgid; r < TT; r += nw) {
;         f32x4 v[8]; float s = 0.f;
;         load_row(p, r, mode, lane, v);
; #pragma unroll
;         for (int j = 0; j < 8; ++j) s += v[j][0] * v[j][0] + v[j][1] * v[j][1] + v[j][2] * v[j][2] + v[j][3] * v[j][3];
;         s = wave_sum(s); const float rs = rsqrtf(s * (1.0f / DM) + EPS);
;         if (mode < 2) {
;             bf16_t* o = (bf16_t*)(p.ws + WS_ABUF) + (size_t)r * DM;
; #pragma unroll
;             for (int j = 0; j < 8; ++j) { const f32x4 gg = ((const f32x4*)g)[j * 64 + lane]; u32x2 w; w.x = pk2(v[j][0] * rs * gg[0], v[j][1] * rs * gg[1]); w.y = pk2(v[j][2] * rs * gg[2], v[j][3] * rs * gg[3]); ((u32x2*)o)[j * 64 + lane] = w; }
;         } else {
; #pragma unroll
;             for (int j = 0; j < 8; ++j) { const f32x4 gg = ((const f32x4*)g)[j * 64 + lane]; ((f32x4*)(X + (size_t)r * DM))[j * 64 + lane] = v[j] * rs * gg; }
;         }
.LBB0_18:
	s_or_b64 exec, exec, s[16:17]
	s_waitcnt vmcnt(0)
	v_mul_f32_e32 v35, v7, v7
	s_waitcnt vmcnt(6)
	v_mul_f32_e32 v53, v3, v3
	v_fmac_f32_e32 v35, v6, v6
	v_fmac_f32_e32 v53, v2, v2
	v_fmac_f32_e32 v35, v8, v8
	v_fmac_f32_e32 v53, v4, v4
	v_fmac_f32_e32 v35, v9, v9
	v_fmac_f32_e32 v53, v5, v5
	v_add_f32_e32 v35, v35, v53
	s_waitcnt vmcnt(5)
	v_mul_f32_e32 v53, v11, v11
	v_fmac_f32_e32 v53, v10, v10
	v_fmac_f32_e32 v53, v12, v12
	v_fmac_f32_e32 v53, v13, v13
	v_add_f32_e32 v35, v53, v35
	s_waitcnt vmcnt(4)
	v_mul_f32_e32 v53, v15, v15
	s_waitcnt vmcnt(2)
	v_pk_mul_f32 v[80:81], v[22:23], v[22:23]
	v_pk_mul_f32 v[82:83], v[18:19], v[18:19]
	v_fmac_f32_e32 v53, v14, v14
	v_pk_mul_f32 v[76:77], v[24:25], v[24:25]
	v_pk_mul_f32 v[78:79], v[20:21], v[20:21]
	v_mov_b32_e32 v84, v80
	v_mov_b32_e32 v85, v82
	v_mov_b32_e32 v82, v81
	v_fmac_f32_e32 v53, v16, v16
	v_pk_add_f32 v[80:81], v[84:85], v[82:83]
	v_mov_b32_e32 v82, v76
	v_mov_b32_e32 v83, v78
	v_fmac_f32_e32 v53, v17, v17
	v_pk_add_f32 v[80:81], v[82:83], v[80:81]
	v_mov_b32_e32 v78, v77
	v_add_f32_e32 v35, v53, v35
	v_pk_add_f32 v[76:77], v[78:79], v[80:81]
	s_waitcnt vmcnt(0)
	v_pk_mul_f32 v[72:73], v[30:31], v[30:31]
	v_pk_mul_f32 v[74:75], v[26:27], v[26:27]
	v_add_f32_e32 v35, v77, v35
	v_pk_mul_f32 v[62:63], v[32:33], v[32:33]
	v_pk_mul_f32 v[64:65], v[28:29], v[28:29]
	v_add_f32_e32 v35, v76, v35
	v_mov_b32_e32 v76, v72
	v_mov_b32_e32 v77, v74
	v_mov_b32_e32 v74, v73
	v_pk_add_f32 v[72:73], v[76:77], v[74:75]
	v_mov_b32_e32 v74, v62
	v_mov_b32_e32 v75, v64
	v_pk_add_f32 v[72:73], v[74:75], v[72:73]
	v_mov_b32_e32 v64, v63
	v_pk_add_f32 v[62:63], v[64:65], v[72:73]
	v_mov_b64_e32 v[72:73], v[204:205]
	v_mov_b64_e32 v[74:75], v[206:207]
	v_add_f32_e32 v35, v63, v35
	v_add_f32_e32 v35, v62, v35
	ds_bpermute_b32 v53, v37, v35
	s_load_dwordx16 s[16:31], s[68:69], 0xc0
	v_mov_b32_e32 v55, v1
	v_mov_b32_e32 v57, v1
	v_add_u32_e32 v34, s8, v34
	s_waitcnt lgkmcnt(0)
	v_add_f32_e32 v35, v35, v53
	ds_bpermute_b32 v53, v66, v35
	v_lshl_add_u64 v[60:61], s[28:29], 0, v[60:61]
	v_lshl_add_u64 v[64:65], v[60:61], 0, v[0:1]
	s_movk_i32 s0, 0x41ff
	v_mov_b32_e32 v59, v1
	s_waitcnt lgkmcnt(0)
	v_add_f32_e32 v35, v35, v53
	ds_bpermute_b32 v53, v67, v35
	v_lshl_add_u64 v[50:51], v[50:51], 0, s[12:13]
	s_waitcnt lgkmcnt(0)
	v_add_f32_e32 v35, v35, v53
	ds_bpermute_b32 v53, v68, v35
	s_waitcnt lgkmcnt(0)
	v_add_f32_e32 v35, v35, v53
	ds_bpermute_b32 v53, v69, v35
	s_waitcnt lgkmcnt(0)
	v_add_f32_e32 v35, v35, v53
	ds_bpermute_b32 v53, v70, v35
	s_waitcnt lgkmcnt(0)
	v_add_f32_e32 v35, v35, v53
	v_fmamk_f32 v35, v35, 0x3a000000, v168
	v_cmp_gt_f32_e32 vcc, s97, v35
	v_mul_f32_e32 v53, 0x4b800000, v35
	s_nop 0
	v_cndmask_b32_e32 v35, v35, v53, vcc
	v_rsq_f32_e32 v35, v35
	s_nop 0
	v_mul_f32_e32 v53, 0x45800000, v35
	v_cndmask_b32_e32 v62, v35, v53, vcc
	v_pk_mul_f32 v[6:7], v[6:7], v[62:63] op_sel_hi:[1,0]
	v_pk_mul_f32 v[8:9], v[8:9], v[62:63] op_sel_hi:[1,0]
	v_pk_mul_f32 v[4:5], v[4:5], v[62:63] op_sel_hi:[1,0]
	v_pk_mul_f32 v[2:3], v[2:3], v[62:63] op_sel_hi:[1,0]
	v_mov_b32_e32 v53, v1
	v_cmp_lt_i32_e32 vcc, s0, v34
	s_or_b64 s[14:15], vcc, s[14:15]
	v_pk_mul_f32 v[8:9], v[74:75], v[8:9]
	v_pk_mul_f32 v[6:7], v[72:73], v[6:7]
	global_store_dwordx4 v[64:65], v[6:9], off
	s_nop 1
	v_mov_b64_e32 v[6:7], v[208:209]
	v_mov_b64_e32 v[8:9], v[210:211]
	v_pk_mul_f32 v[2:3], v[6:7], v[2:3]
	v_pk_mul_f32 v[4:5], v[8:9], v[4:5]
	global_store_dwordx4 v[64:65], v[2:5], off offset:1024
	s_nop 1
	v_mov_b64_e32 v[2:3], v[212:213]
	v_mov_b64_e32 v[4:5], v[214:215]
	v_pk_mul_f32 v[6:7], v[12:13], v[62:63] op_sel_hi:[1,0]
	v_pk_mul_f32 v[8:9], v[10:11], v[62:63] op_sel_hi:[1,0]
	v_pk_mul_f32 v[4:5], v[4:5], v[6:7]
	v_pk_mul_f32 v[2:3], v[2:3], v[8:9]
	global_store_dwordx4 v[64:65], v[2:5], off offset:2048
	s_nop 1
	v_mov_b64_e32 v[2:3], v[216:217]
	v_mov_b64_e32 v[4:5], v[218:219]
	v_pk_mul_f32 v[6:7], v[16:17], v[62:63] op_sel_hi:[1,0]
	v_pk_mul_f32 v[8:9], v[14:15], v[62:63] op_sel_hi:[1,0]
	v_pk_mul_f32 v[4:5], v[4:5], v[6:7]
	v_pk_mul_f32 v[2:3], v[2:3], v[8:9]
	global_store_dwordx4 v[64:65], v[2:5], off offset:3072
	s_nop 1
	v_mov_b64_e32 v[2:3], v[220:221]
	v_mov_b64_e32 v[4:5], v[222:223]
	v_pk_mul_f32 v[6:7], v[20:21], v[62:63] op_sel_hi:[1,0]
	v_pk_mul_f32 v[8:9], v[18:19], v[62:63] op_sel_hi:[1,0]
	v_pk_mul_f32 v[4:5], v[4:5], v[6:7]
	v_pk_mul_f32 v[2:3], v[2:3], v[8:9]
	v_lshl_add_u64 v[6:7], v[60:61], 0, v[52:53]
	global_store_dwordx4 v[6:7], v[2:5], off
	s_nop 1
	v_mov_b64_e32 v[2:3], v[224:225]
	v_mov_b64_e32 v[4:5], v[226:227]
	v_pk_mul_f32 v[6:7], v[24:25], v[62:63] op_sel_hi:[1,0]
	v_pk_mul_f32 v[8:9], v[22:23], v[62:63] op_sel_hi:[1,0]
	v_pk_mul_f32 v[4:5], v[4:5], v[6:7]
	v_pk_mul_f32 v[2:3], v[2:3], v[8:9]
	v_lshl_add_u64 v[6:7], v[60:61], 0, v[54:55]
	global_store_dwordx4 v[6:7], v[2:5], off
	s_nop 1
	v_mov_b64_e32 v[2:3], v[228:229]
	v_mov_b64_e32 v[4:5], v[230:231]
	v_pk_mul_f32 v[6:7], v[28:29], v[62:63] op_sel_hi:[1,0]
	v_pk_mul_f32 v[8:9], v[26:27], v[62:63] op_sel_hi:[1,0]
	v_pk_mul_f32 v[4:5], v[4:5], v[6:7]
	v_pk_mul_f32 v[2:3], v[2:3], v[8:9]
	v_lshl_add_u64 v[6:7], v[60:61], 0, v[56:57]
	global_store_dwordx4 v[6:7], v[2:5], off
	s_nop 1
	v_mov_b64_e32 v[2:3], v[232:233]
	v_mov_b64_e32 v[4:5], v[234:235]
	v_pk_mul_f32 v[6:7], v[32:33], v[62:63] op_sel_hi:[1,0]
	v_pk_mul_f32 v[8:9], v[30:31], v[62:63] op_sel_hi:[1,0]
	v_pk_mul_f32 v[4:5], v[4:5], v[6:7]
	v_pk_mul_f32 v[2:3], v[2:3], v[8:9]
	v_lshl_add_u64 v[6:7], v[60:61], 0, v[58:59]
	global_store_dwordx4 v[6:7], v[2:5], off
	s_andn2_b64 exec, exec, s[14:15]
	s_cbranch_execz .LBB0_23

; __device__ __forceinline__ unsigned pk2(float lo, float hi) { unsigned r; asm("v_cvt_pk_bf16_f32 %0, %1, %2" : "=v"(r) : "v"(lo), "v"(hi)); return r; }
; __device__ __forceinline__ void load_row(const Params& p, int r, int mode, int lane, f32x4 (&v)[8]) {
;     float* X = p.out;
;     if (r < TP) {
; #pragma unroll
;         for (int j = 0; j < 8; ++j) v[j] = ((const f32x4*)(X + (size_t)r * DM))[j * 64 + lane];
;     } else {
;         const float* base = mode == 0 ? p.in[1] + (size_t)(r - TP) * DM : X + (size_t)r * DM;
;         const float alpha = mode == 1 ? 1.0f : 0.5f;
;         const float* P = (const float*)(p.ws + WS_PART) + (size_t)(r - TP) * DM;
; #pragma unroll
;         for (int j = 0; j < 8; ++j) {
;             f32x4 a = (f32x4){0.f, 0.f, 0.f, 0.f};
; #pragma unroll
;             for (int q = 0; q < 8; ++q) a += ((const f32x4*)(P + (size_t)q * 512 * DM))[j * 64 + lane];
;             v[j] = ((const f32x4*)base)[j * 64 + lane] + alpha * a;
;             if (mode < 2) ((f32x4*)(X + (size_t)r * DM))[j * 64 + lane] = v[j];
;         }
;     }
; }
; __device__ __forceinline__ void phase_norm(const Params& p, unsigned char* sm, int mode, const int TIDX, const int BIDX) {
;     const int tid = TIDX, wid = tid >> 6, lane = tid & 63, wgid = BIDX * 8 + wid, nw = gridDim.x * 8;
;     float* X = p.out;
;     const float* g = mode == 0 ? p.in[12] : (mode == 1 ? p.in[26] : p.in[29]);
;     for (int r = wgid; r < TT; r += nw) {
;         f32x4 v[8]; float s = 0.f;
;         load_row(p, r, mode, lane, v);
; #pragma unroll
;         for (int j = 0; j < 8; ++j) s += v[j][0] * v[j][0] + v[j][1] * v[j][1] + v[j][2] * v[j][2] + v[j][3] * v[j][3];
;         s = wave_sum(s); const float rs = rsqrtf(s * (1.0f / DM) + EPS);
;         if (mode < 2) {
;             bf16_t* o = (bf16_t*)(p.ws + WS_ABUF) + (size_t)r * DM;
; #pragma unroll
;             for (int j = 0; j < 8; ++j) { const f32x4 gg = ((const f32x4*)g)[j * 64 + lane]; u32x2 w; w.x = pk2(v[j][0] * rs * gg[0], v[j][1] * rs * gg[1]); w.y = pk2(v[j][2] * rs * gg[2], v[j][3] * rs * gg[3]); ((u32x2*)o)[j * 64 + lane] = w; }
.LBB0_26:
	s_and_b64 vcc, exec, s[8:9]
	s_cbranch_vccz .LBB0_35
	v_readlane_b32 s0, v254, 41
	v_ashrrev_i32_e32 v2, 6, v199
	s_lshl_b32 s14, s0, 3
	v_add_u32_e32 v0, s14, v2
	s_movk_i32 s0, 0x4200
	v_cmp_gt_i32_e32 vcc, s0, v0
	s_and_saveexec_b64 s[8:9], vcc
	s_cbranch_execz .LBB0_34
	v_readlane_b32 s10, v254, 4
	v_readlane_b32 s11, v254, 5
	s_load_dword s0, s[10:11], 0x0
	s_load_dwordx16 s[16:31], s[68:69], 0xc0
	v_cmp_lt_i32_e32 vcc, v189, v188
	v_and_b32_e32 v4, 63, v199
	v_or_b32_e32 v6, 0x100, v4
	v_cndmask_b32_e32 v0, v169, v189, vcc
	v_cmp_lt_i32_e32 vcc, v190, v188
	v_lshlrev_b32_e32 v64, 2, v0
	s_waitcnt lgkmcnt(0)
	s_lshl_b32 s10, s0, 3
	v_cndmask_b32_e32 v0, v169, v190, vcc
	v_cmp_lt_i32_e32 vcc, v191, v188
	v_lshlrev_b32_e32 v65, 2, v0
	v_or_b32_e32 v8, 0x140, v4
	v_cndmask_b32_e32 v0, v169, v191, vcc
	v_cmp_lt_i32_e32 vcc, v192, v188
	v_lshlrev_b32_e32 v66, 2, v0
	v_lshlrev_b32_e32 v14, 4, v6
	v_cndmask_b32_e32 v0, v169, v192, vcc
	v_cmp_lt_i32_e32 vcc, v193, v188
	v_mov_b32_e32 v15, v1
	s_add_u32 s12, s30, 0x1afe4000
	v_or_b32_e32 v10, 0x180, v4
	v_lshlrev_b32_e32 v67, 2, v0
	v_cndmask_b32_e32 v0, v169, v193, vcc
	v_cmp_lt_i32_e32 vcc, v194, v188
	v_lshl_add_u64 v[36:37], s[20:21], 0, v[14:15]
	v_lshlrev_b32_e32 v14, 4, v8
	s_addc_u32 s13, s31, 0
	v_ashrrev_i32_e32 v3, 31, v2
	s_ashr_i32 s15, s14, 31
	v_or_b32_e32 v12, 0x1c0, v4
	v_lshlrev_b32_e32 v68, 2, v0
	v_cndmask_b32_e32 v0, v169, v194, vcc
	v_lshl_add_u64 v[38:39], s[20:21], 0, v[14:15]
	v_lshlrev_b32_e32 v14, 4, v10
	v_lshl_add_u64 v[46:47], v[2:3], 0, s[14:15]
	v_lshlrev_b32_e32 v69, 2, v0
	v_lshlrev_b32_e32 v0, 4, v4
	v_lshl_add_u64 v[40:41], s[20:21], 0, v[14:15]
	v_lshlrev_b32_e32 v14, 4, v12
	v_lshlrev_b64 v[2:3], 13, v[46:47]
	v_lshl_add_u64 v[42:43], s[20:21], 0, v[14:15]
	v_lshlrev_b32_e32 v14, 3, v4
	v_or_b32_e32 v2, v2, v0
	v_lshl_add_u64 v[14:15], s[30:31], 0, v[14:15]
	s_mov_b64 s[16:17], 0x6284000
	s_ashr_i32 s11, s10, 31
	v_lshl_add_u64 v[2:3], s[28:29], 0, v[2:3]
	s_mov_b64 s[14:15], 0x1000
	v_lshl_add_u64 v[34:35], s[20:21], 0, v[0:1]
	v_lshl_add_u64 v[44:45], v[14:15], 0, s[16:17]
	v_lshl_add_u64 v[48:49], v[2:3], 0, s[14:15]
	s_lshl_b64 s[14:15], s[10:11], 13
	s_mov_b64 s[16:17], 0
	v_lshlrev_b32_e32 v50, 4, v4
	v_lshlrev_b32_e32 v52, 4, v6
	v_lshlrev_b32_e32 v54, 4, v8
	v_lshlrev_b32_e32 v56, 4, v10
	v_lshlrev_b32_e32 v58, 4, v12
	global_load_dwordx4 v[204:207], v[34:35], off
	global_load_dwordx4 v[208:211], v[34:35], off offset:1024
	global_load_dwordx4 v[212:215], v[34:35], off offset:2048
	global_load_dwordx4 v[216:219], v[34:35], off offset:3072
	global_load_dwordx4 v[220:223], v[36:37], off
	global_load_dwordx4 v[224:227], v[38:39], off
	global_load_dwordx4 v[228:231], v[40:41], off
	global_load_dwordx4 v[232:235], v[42:43], off
	s_waitcnt vmcnt(0)
	s_branch .LBB0_30
.LBB0_29:
	s_or_b64 exec, exec, s[18:19]
	s_waitcnt vmcnt(0)
	v_mul_f32_e32 v0, v3, v3
	s_waitcnt vmcnt(6)
	v_mul_f32_e32 v51, v7, v7
	v_fmac_f32_e32 v0, v2, v2
	v_fmac_f32_e32 v51, v6, v6
	v_fmac_f32_e32 v0, v4, v4
	v_fmac_f32_e32 v51, v8, v8
	v_fmac_f32_e32 v0, v5, v5
	v_fmac_f32_e32 v51, v9, v9
	v_add_f32_e32 v0, v0, v51
	s_waitcnt vmcnt(5)
	v_mul_f32_e32 v51, v11, v11
	v_fmac_f32_e32 v51, v10, v10
	v_fmac_f32_e32 v51, v12, v12
	v_fmac_f32_e32 v51, v13, v13
	v_add_f32_e32 v0, v51, v0
	s_waitcnt vmcnt(4)
	v_mul_f32_e32 v51, v15, v15
	s_waitcnt vmcnt(2)
	v_pk_mul_f32 v[80:81], v[22:23], v[22:23]
	v_pk_mul_f32 v[82:83], v[18:19], v[18:19]
	v_fmac_f32_e32 v51, v14, v14
	v_pk_mul_f32 v[76:77], v[24:25], v[24:25]
	v_pk_mul_f32 v[78:79], v[20:21], v[20:21]
	v_mov_b32_e32 v84, v80
	v_mov_b32_e32 v85, v82
	v_mov_b32_e32 v82, v81
	v_fmac_f32_e32 v51, v16, v16
	v_pk_add_f32 v[80:81], v[84:85], v[82:83]
	v_mov_b32_e32 v82, v76
	v_mov_b32_e32 v83, v78
	v_fmac_f32_e32 v51, v17, v17
	v_pk_add_f32 v[80:81], v[82:83], v[80:81]
	v_mov_b32_e32 v78, v77
	v_add_f32_e32 v0, v51, v0
	v_pk_add_f32 v[76:77], v[78:79], v[80:81]
	s_waitcnt vmcnt(0)
	v_pk_mul_f32 v[72:73], v[30:31], v[30:31]
	v_pk_mul_f32 v[74:75], v[26:27], v[26:27]
	v_add_f32_e32 v0, v77, v0
	v_pk_mul_f32 v[62:63], v[32:33], v[32:33]
	v_pk_mul_f32 v[70:71], v[28:29], v[28:29]
	v_add_f32_e32 v0, v76, v0
	v_mov_b32_e32 v76, v72
	v_mov_b32_e32 v77, v74
	v_mov_b32_e32 v74, v73
	v_pk_add_f32 v[72:73], v[76:77], v[74:75]
	v_mov_b32_e32 v74, v62
	v_mov_b32_e32 v75, v70
	v_pk_add_f32 v[72:73], v[74:75], v[72:73]
	v_mov_b32_e32 v70, v63
	v_pk_add_f32 v[62:63], v[70:71], v[72:73]
	v_mov_b64_e32 v[70:71], v[204:205]
	v_mov_b64_e32 v[72:73], v[206:207]
	v_add_f32_e32 v0, v63, v0
	v_add_f32_e32 v0, v62, v0
	ds_bpermute_b32 v51, v64, v0
	v_lshlrev_b64 v[60:61], 12, v[60:61]
	v_lshl_add_u64 v[46:47], v[46:47], 0, s[10:11]
	s_movk_i32 s0, 0x41ff
	v_lshl_add_u64 v[48:49], v[48:49], 0, s[14:15]
	s_waitcnt lgkmcnt(0)
	v_add_f32_e32 v0, v0, v51
	ds_bpermute_b32 v51, v65, v0
	s_waitcnt lgkmcnt(0)
	v_add_f32_e32 v0, v0, v51
	ds_bpermute_b32 v51, v66, v0
	s_waitcnt lgkmcnt(0)
	v_add_f32_e32 v0, v0, v51
	ds_bpermute_b32 v51, v67, v0
	s_waitcnt lgkmcnt(0)
	v_add_f32_e32 v0, v0, v51
	ds_bpermute_b32 v51, v68, v0
	s_waitcnt lgkmcnt(0)
	v_add_f32_e32 v0, v0, v51
	ds_bpermute_b32 v51, v69, v0
	s_waitcnt lgkmcnt(0)
; __device__ __forceinline__ unsigned pk2(float lo, float hi) { unsigned r; asm("v_cvt_pk_bf16_f32 %0, %1, %2" : "=v"(r) : "v"(lo), "v"(hi)); return r; }
; __device__ __forceinline__ void load_row(const Params& p, int r, int mode, int lane, f32x4 (&v)[8]) {
;     float* X = p.out;
;     if (r < TP) {
; #pragma unroll
;         for (int j = 0; j < 8; ++j) v[j] = ((const f32x4*)(X + (size_t)r * DM))[j * 64 + lane];
;     } else {
;         const float* base = mode == 0 ? p.in[1] + (size_t)(r - TP) * DM : X + (size_t)r * DM;
;         const float alpha = mode == 1 ? 1.0f : 0.5f;
;         const float* P = (const float*)(p.ws + WS_PART) + (size_t)(r - TP) * DM;
; #pragma unroll
;         for (int j = 0; j < 8; ++j) {
;             f32x4 a = (f32x4){0.f, 0.f, 0.f, 0.f};
; #pragma unroll
;             for (int q = 0; q < 8; ++q) a += ((const f32x4*)(P + (size_t)q * 512 * DM))[j * 64 + lane];
;             v[j] = ((const f32x4*)base)[j * 64 + lane] + alpha * a;
;             if (mode < 2) ((f32x4*)(X + (size_t)r * DM))[j * 64 + lane] = v[j];
;         }
;     }
; }
; __device__ __forceinline__ void phase_norm(const Params& p, unsigned char* sm, int mode, const int TIDX, const int BIDX) {
;     const int tid = TIDX, wid = tid >> 6, lane = tid & 63, wgid = BIDX * 8 + wid, nw = gridDim.x * 8;
;     float* X = p.out;
;     const float* g = mode == 0 ? p.in[12] : (mode == 1 ? p.in[26] : p.in[29]);
;     for (int r = wgid; r < TT; r += nw) {
;         f32x4 v[8]; float s = 0.f;
;         load_row(p, r, mode, lane, v);
; #pragma unroll
;         for (int j = 0; j < 8; ++j) s += v[j][0] * v[j][0] + v[j][1] * v[j][1] + v[j][2] * v[j][2] + v[j][3] * v[j][3];
;         s = wave_sum(s); const float rs = rsqrtf(s * (1.0f / DM) + EPS);
;         if (mode < 2) {
;             bf16_t* o = (bf16_t*)(p.ws + WS_ABUF) + (size_t)r * DM;
; #pragma unroll
;             for (int j = 0; j < 8; ++j) { const f32x4 gg = ((const f32x4*)g)[j * 64 + lane]; u32x2 w; w.x = pk2(v[j][0] * rs * gg[0], v[j][1] * rs * gg[1]); w.y = pk2(v[j][2] * rs * gg[2], v[j][3] * rs * gg[3]); ((u32x2*)o)[j * 64 + lane] = w; }
	v_add_f32_e32 v0, v0, v51
	v_fmamk_f32 v0, v0, 0x3a000000, v168
	v_cmp_gt_f32_e32 vcc, s97, v0
	v_mul_f32_e32 v51, 0x4b800000, v0
	s_nop 0
	v_cndmask_b32_e32 v0, v0, v51, vcc
	v_rsq_f32_e32 v0, v0
	s_nop 0
	v_mul_f32_e32 v51, 0x45800000, v0
	v_cndmask_b32_e32 v0, v0, v51, vcc
	v_mul_f32_e32 v2, v2, v0
	v_mul_f32_e32 v3, v3, v0
	v_cmp_lt_i32_e32 vcc, s0, v46
	s_or_b64 s[16:17], vcc, s[16:17]
	v_mul_f32_e32 v2, v70, v2
	v_mul_f32_e32 v3, v71, v3
	v_cvt_pk_bf16_f32 v62, v2, v3
	v_mul_f32_e32 v2, v4, v0
	v_mul_f32_e32 v3, v5, v0
	v_mul_f32_e32 v2, v72, v2
	v_mul_f32_e32 v3, v73, v3
	v_cvt_pk_bf16_f32 v63, v2, v3
	v_lshl_add_u64 v[2:3], v[44:45], 0, v[60:61]
	global_store_dwordx2 v[2:3], v[62:63], off
	v_mov_b64_e32 v[60:61], v[208:209]
	v_mov_b64_e32 v[62:63], v[210:211]
	v_mul_f32_e32 v4, v6, v0
	v_mul_f32_e32 v5, v7, v0
	v_mul_f32_e32 v6, v9, v0
	v_mul_f32_e32 v4, v60, v4
	v_mul_f32_e32 v5, v61, v5
	v_cvt_pk_bf16_f32 v4, v4, v5
	v_mul_f32_e32 v5, v8, v0
	v_mul_f32_e32 v5, v62, v5
	v_mul_f32_e32 v6, v63, v6
	v_cvt_pk_bf16_f32 v5, v5, v6
	global_store_dwordx2 v[2:3], v[4:5], off offset:512
	v_mov_b64_e32 v[4:5], v[212:213]
	v_mov_b64_e32 v[6:7], v[214:215]
	v_mul_f32_e32 v8, v10, v0
	v_mul_f32_e32 v4, v4, v8
	v_mul_f32_e32 v8, v11, v0
	v_mul_f32_e32 v5, v5, v8
	v_cvt_pk_bf16_f32 v4, v4, v5
	v_mul_f32_e32 v5, v12, v0
	v_mul_f32_e32 v5, v6, v5
	v_mul_f32_e32 v6, v13, v0
	v_mul_f32_e32 v6, v7, v6
	v_cvt_pk_bf16_f32 v5, v5, v6
	global_store_dwordx2 v[2:3], v[4:5], off offset:1024
	v_mov_b64_e32 v[4:5], v[216:217]
	v_mov_b64_e32 v[6:7], v[218:219]
	v_mul_f32_e32 v8, v14, v0
	v_mul_f32_e32 v4, v4, v8
	v_mul_f32_e32 v8, v15, v0
	v_mul_f32_e32 v5, v5, v8
	v_cvt_pk_bf16_f32 v4, v4, v5
	v_mul_f32_e32 v5, v16, v0
	v_mul_f32_e32 v5, v6, v5
	v_mul_f32_e32 v6, v17, v0
	v_mul_f32_e32 v6, v7, v6
	v_cvt_pk_bf16_f32 v5, v5, v6
	global_store_dwordx2 v[2:3], v[4:5], off offset:1536
	v_mov_b64_e32 v[4:5], v[220:221]
	v_mov_b64_e32 v[6:7], v[222:223]
	v_mul_f32_e32 v8, v18, v0
	v_mul_f32_e32 v4, v4, v8
	v_mul_f32_e32 v8, v19, v0
	v_mul_f32_e32 v5, v5, v8
	v_cvt_pk_bf16_f32 v4, v4, v5
	v_mul_f32_e32 v5, v20, v0
	v_mul_f32_e32 v5, v6, v5
	v_mul_f32_e32 v6, v21, v0
	v_mul_f32_e32 v6, v7, v6
	v_cvt_pk_bf16_f32 v5, v5, v6
	global_store_dwordx2 v[2:3], v[4:5], off offset:2048
	v_mov_b64_e32 v[4:5], v[224:225]
	v_mov_b64_e32 v[6:7], v[226:227]
	v_mul_f32_e32 v8, v22, v0
	v_mul_f32_e32 v4, v8, v4
	v_mul_f32_e32 v8, v23, v0
	v_mul_f32_e32 v5, v8, v5
	v_cvt_pk_bf16_f32 v4, v4, v5
	v_mul_f32_e32 v5, v24, v0
	v_mul_f32_e32 v5, v5, v6
	v_mul_f32_e32 v6, v25, v0
	v_mul_f32_e32 v6, v6, v7
	v_cvt_pk_bf16_f32 v5, v5, v6
	global_store_dwordx2 v[2:3], v[4:5], off offset:2560
	v_mov_b64_e32 v[4:5], v[228:229]
	v_mov_b64_e32 v[6:7], v[230:231]
	v_mul_f32_e32 v8, v26, v0
	v_mul_f32_e32 v4, v8, v4
	v_mul_f32_e32 v8, v27, v0
	v_mul_f32_e32 v5, v8, v5
	v_cvt_pk_bf16_f32 v4, v4, v5
	v_mul_f32_e32 v5, v28, v0
	v_mul_f32_e32 v5, v5, v6
	v_mul_f32_e32 v6, v29, v0
	v_mul_f32_e32 v6, v6, v7
	v_cvt_pk_bf16_f32 v5, v5, v6
	global_store_dwordx2 v[2:3], v[4:5], off offset:3072
	v_mov_b64_e32 v[4:5], v[232:233]
	v_mov_b64_e32 v[6:7], v[234:235]
	v_mul_f32_e32 v8, v30, v0
	v_mul_f32_e32 v4, v8, v4
	v_mul_f32_e32 v8, v31, v0
	v_mul_f32_e32 v5, v8, v5
	v_cvt_pk_bf16_f32 v4, v4, v5
	v_mul_f32_e32 v5, v32, v0
	v_mul_f32_e32 v5, v5, v6
	v_mul_f32_e32 v0, v33, v0
	v_mul_f32_e32 v0, v0, v7
	v_cvt_pk_bf16_f32 v5, v5, v0
	global_store_dwordx2 v[2:3], v[4:5], off offset:3584
	s_andn2_b64 exec, exec, s[16:17]
	s_cbranch_execz .LBB0_34
.LBB0_30:
	v_cmp_lt_i32_e32 vcc, s81, v46
	s_and_saveexec_b64 s[18:19], vcc
	s_xor_b64 s[18:19], exec, s[18:19]
	s_cbranch_execz .LBB0_32
	s_load_dwordx2 s[52:53], s[68:69], 0xf0
	v_mov_b32_e32 v0, v46
	v_lshlrev_b64 v[2:3], 13, v[0:1]
	v_mov_b32_e32 v51, v1
	s_waitcnt vmcnt(0) lgkmcnt(0)
	v_lshl_add_u64 v[150:151], s[52:53], 0, v[2:3]
	v_lshl_add_u64 v[150:151], v[150:151], 0, v[50:51]
	v_add_u32_e32 v2, 0xffffc000, v46
	v_mov_b32_e32 v3, v1
	v_lshlrev_b64 v[2:3], 13, v[2:3]
	v_lshl_add_u64 v[152:153], s[12:13], 0, v[2:3]
	v_lshl_add_u64 v[152:153], v[152:153], 0, v[50:51]
	s_mov_b32 s20, 0x400000
	s_mov_b32 s21, 0
	s_mov_b32 s22, 0x1000
	s_mov_b32 s23, 0
	v_mov_b64_e32 v[148:149], v[152:153]
	v_mov_b64_e32 v[154:155], v[150:151]
	global_load_dwordx4 v[76:79], v[148:149], off
	global_load_dwordx4 v[80:83], v[148:149], off offset:1024
	v_lshl_add_u64 v[148:149], v[148:149], 0, s[20:21]
	global_load_dwordx4 v[84:87], v[148:149], off
	global_load_dwordx4 v[88:91], v[148:149], off offset:1024
	v_lshl_add_u64 v[148:149], v[148:149], 0, s[20:21]
	global_load_dwordx4 v[92:95], v[148:149], off
	global_load_dwordx4 v[96:99], v[148:149], off offset:1024
	v_lshl_add_u64 v[148:149], v[148:149], 0, s[20:21]
	global_load_dwordx4 v[100:103], v[148:149], off
	global_load_dwordx4 v[104:107], v[148:149], off offset:1024
	v_lshl_add_u64 v[148:149], v[148:149], 0, s[20:21]
	global_load_dwordx4 v[108:111], v[148:149], off
	global_load_dwordx4 v[112:115], v[148:149], off offset:1024
	v_lshl_add_u64 v[148:149], v[148:149], 0, s[20:21]
	global_load_dwordx4 v[116:119], v[148:149], off
	global_load_dwordx4 v[120:123], v[148:149], off offset:1024
	v_lshl_add_u64 v[148:149], v[148:149], 0, s[20:21]
	global_load_dwordx4 v[124:127], v[148:149], off
	global_load_dwordx4 v[128:131], v[148:149], off offset:1024
	v_lshl_add_u64 v[148:149], v[148:149], 0, s[20:21]
	global_load_dwordx4 v[132:135], v[148:149], off
	global_load_dwordx4 v[136:139], v[148:149], off offset:1024
	global_load_dwordx4 v[140:143], v[154:155], off
	global_load_dwordx4 v[144:147], v[154:155], off offset:1024
	s_waitcnt vmcnt(0)
; __device__ __forceinline__ void load_row(const Params& p, int r, int mode, int lane, f32x4 (&v)[8]) {
;     ...
;         const float* P = (const float*)(p.ws + WS_PART) + (size_t)(r - TP) * DM;
; #pragma unroll
;         for (int j = 0; j < 8; ++j) {
;             f32x4 a = (f32x4){0.f, 0.f, 0.f, 0.f};
; #pragma unroll
;             for (int q = 0; q < 8; ++q) a += ((const f32x4*)(P + (size_t)q * 512 * DM))[j * 64 + lane];
;             v[j] = ((const f32x4*)base)[j * 64 + lane] + alpha * a;
;             if (mode < 2) ((f32x4*)(X + (size_t)r * DM))[j * 64 + lane] = v[j];
;         }
	v_pk_add_f32 v[78:79], v[78:79], 0 op_sel_hi:[1,0]
	v_pk_add_f32 v[76:77], v[76:77], 0 op_sel_hi:[1,0]
	v_pk_add_f32 v[78:79], v[78:79], v[86:87]
	v_pk_add_f32 v[76:77], v[76:77], v[84:85]
	v_pk_add_f32 v[78:79], v[78:79], v[94:95]
	v_pk_add_f32 v[76:77], v[76:77], v[92:93]
	v_pk_add_f32 v[78:79], v[78:79], v[102:103]
	v_pk_add_f32 v[76:77], v[76:77], v[100:101]
	v_pk_add_f32 v[78:79], v[78:79], v[110:111]
	v_pk_add_f32 v[76:77], v[76:77], v[108:109]
	v_pk_add_f32 v[78:79], v[78:79], v[118:119]
	v_pk_add_f32 v[76:77], v[76:77], v[116:117]
	v_pk_add_f32 v[78:79], v[78:79], v[126:127]
	v_pk_add_f32 v[76:77], v[76:77], v[124:125]
	v_pk_add_f32 v[78:79], v[78:79], v[134:135]
	v_pk_add_f32 v[76:77], v[76:77], v[132:133]
	v_pk_add_f32 v[4:5], v[142:143], v[78:79]
	v_pk_add_f32 v[2:3], v[140:141], v[76:77]
	global_store_dwordx4 v[154:155], v[2:5], off
	v_pk_add_f32 v[82:83], v[82:83], 0 op_sel_hi:[1,0]
	v_pk_add_f32 v[80:81], v[80:81], 0 op_sel_hi:[1,0]
	v_pk_add_f32 v[82:83], v[82:83], v[90:91]
	v_pk_add_f32 v[80:81], v[80:81], v[88:89]
	v_pk_add_f32 v[82:83], v[82:83], v[98:99]
	v_pk_add_f32 v[80:81], v[80:81], v[96:97]
	v_pk_add_f32 v[82:83], v[82:83], v[106:107]
	v_pk_add_f32 v[80:81], v[80:81], v[104:105]
	v_pk_add_f32 v[82:83], v[82:83], v[114:115]
	v_pk_add_f32 v[80:81], v[80:81], v[112:113]
	v_pk_add_f32 v[82:83], v[82:83], v[122:123]
	v_pk_add_f32 v[80:81], v[80:81], v[120:121]
	v_pk_add_f32 v[82:83], v[82:83], v[130:131]
	v_pk_add_f32 v[80:81], v[80:81], v[128:129]
	v_pk_add_f32 v[82:83], v[82:83], v[138:139]
	v_pk_add_f32 v[80:81], v[80:81], v[136:137]
	v_pk_add_f32 v[8:9], v[146:147], v[82:83]
	v_pk_add_f32 v[6:7], v[144:145], v[80:81]
	global_store_dwordx4 v[154:155], v[6:9], off offset:1024
	v_mov_b64_e32 v[148:149], v[152:153]
	v_mov_b64_e32 v[154:155], v[150:151]
	global_load_dwordx4 v[76:79], v[148:149], off offset:2048
	global_load_dwordx4 v[80:83], v[148:149], off offset:3072
	v_lshl_add_u64 v[148:149], v[148:149], 0, s[20:21]
	global_load_dwordx4 v[84:87], v[148:149], off offset:2048
	global_load_dwordx4 v[88:91], v[148:149], off offset:3072
	v_lshl_add_u64 v[148:149], v[148:149], 0, s[20:21]
	global_load_dwordx4 v[92:95], v[148:149], off offset:2048
	global_load_dwordx4 v[96:99], v[148:149], off offset:3072
	v_lshl_add_u64 v[148:149], v[148:149], 0, s[20:21]
	global_load_dwordx4 v[100:103], v[148:149], off offset:2048
	global_load_dwordx4 v[104:107], v[148:149], off offset:3072
	v_lshl_add_u64 v[148:149], v[148:149], 0, s[20:21]
	global_load_dwordx4 v[108:111], v[148:149], off offset:2048
	global_load_dwordx4 v[112:115], v[148:149], off offset:3072
	v_lshl_add_u64 v[148:149], v[148:149], 0, s[20:21]
	global_load_dwordx4 v[116:119], v[148:149], off offset:2048
	global_load_dwordx4 v[120:123], v[148:149], off offset:3072
	v_lshl_add_u64 v[148:149], v[148:149], 0, s[20:21]
	global_load_dwordx4 v[124:127], v[148:149], off offset:2048
	global_load_dwordx4 v[128:131], v[148:149], off offset:3072
	v_lshl_add_u64 v[148:149], v[148:149], 0, s[20:21]
	global_load_dwordx4 v[132:135], v[148:149], off offset:2048
	global_load_dwordx4 v[136:139], v[148:149], off offset:3072
	global_load_dwordx4 v[140:143], v[154:155], off offset:2048
	global_load_dwordx4 v[144:147], v[154:155], off offset:3072
	s_waitcnt vmcnt(0)
	v_pk_add_f32 v[78:79], v[78:79], 0 op_sel_hi:[1,0]
	v_pk_add_f32 v[76:77], v[76:77], 0 op_sel_hi:[1,0]
	v_pk_add_f32 v[78:79], v[78:79], v[86:87]
	v_pk_add_f32 v[76:77], v[76:77], v[84:85]
	v_pk_add_f32 v[78:79], v[78:79], v[94:95]
	v_pk_add_f32 v[76:77], v[76:77], v[92:93]
	v_pk_add_f32 v[78:79], v[78:79], v[102:103]
	v_pk_add_f32 v[76:77], v[76:77], v[100:101]
	v_pk_add_f32 v[78:79], v[78:79], v[110:111]
	v_pk_add_f32 v[76:77], v[76:77], v[108:109]
	v_pk_add_f32 v[78:79], v[78:79], v[118:119]
	v_pk_add_f32 v[76:77], v[76:77], v[116:117]
	v_pk_add_f32 v[78:79], v[78:79], v[126:127]
	v_pk_add_f32 v[76:77], v[76:77], v[124:125]
	v_pk_add_f32 v[78:79], v[78:79], v[134:135]
	v_pk_add_f32 v[76:77], v[76:77], v[132:133]
	v_pk_add_f32 v[12:13], v[142:143], v[78:79]
	v_pk_add_f32 v[10:11], v[140:141], v[76:77]
	global_store_dwordx4 v[154:155], v[10:13], off offset:2048
	v_pk_add_f32 v[82:83], v[82:83], 0 op_sel_hi:[1,0]
	v_pk_add_f32 v[80:81], v[80:81], 0 op_sel_hi:[1,0]
	v_pk_add_f32 v[82:83], v[82:83], v[90:91]
	v_pk_add_f32 v[80:81], v[80:81], v[88:89]
	v_pk_add_f32 v[82:83], v[82:83], v[98:99]
	v_pk_add_f32 v[80:81], v[80:81], v[96:97]
	v_pk_add_f32 v[82:83], v[82:83], v[106:107]
	v_pk_add_f32 v[80:81], v[80:81], v[104:105]
	v_pk_add_f32 v[82:83], v[82:83], v[114:115]
	v_pk_add_f32 v[80:81], v[80:81], v[112:113]
	v_pk_add_f32 v[82:83], v[82:83], v[122:123]
	v_pk_add_f32 v[80:81], v[80:81], v[120:121]
	v_pk_add_f32 v[82:83], v[82:83], v[130:131]
	v_pk_add_f32 v[80:81], v[80:81], v[128:129]
	v_pk_add_f32 v[82:83], v[82:83], v[138:139]
	v_pk_add_f32 v[80:81], v[80:81], v[136:137]
	v_pk_add_f32 v[16:17], v[146:147], v[82:83]
	v_pk_add_f32 v[14:15], v[144:145], v[80:81]
	global_store_dwordx4 v[154:155], v[14:17], off offset:3072
	v_lshl_add_u64 v[148:149], v[152:153], 0, s[22:23]
	v_lshl_add_u64 v[154:155], v[150:151], 0, s[22:23]
	global_load_dwordx4 v[76:79], v[148:149], off
	global_load_dwordx4 v[80:83], v[148:149], off offset:1024
	v_lshl_add_u64 v[148:149], v[148:149], 0, s[20:21]
	global_load_dwordx4 v[84:87], v[148:149], off
	global_load_dwordx4 v[88:91], v[148:149], off offset:1024
	v_lshl_add_u64 v[148:149], v[148:149], 0, s[20:21]
	global_load_dwordx4 v[92:95], v[148:149], off
	global_load_dwordx4 v[96:99], v[148:149], off offset:1024
	v_lshl_add_u64 v[148:149], v[148:149], 0, s[20:21]
	global_load_dwordx4 v[100:103], v[148:149], off
	global_load_dwordx4 v[104:107], v[148:149], off offset:1024
	v_lshl_add_u64 v[148:149], v[148:149], 0, s[20:21]
	global_load_dwordx4 v[108:111], v[148:149], off
	global_load_dwordx4 v[112:115], v[148:149], off offset:1024
	v_lshl_add_u64 v[148:149], v[148:149], 0, s[20:21]
	global_load_dwordx4 v[116:119], v[148:149], off
	global_load_dwordx4 v[120:123], v[148:149], off offset:1024
	v_lshl_add_u64 v[148:149], v[148:149], 0, s[20:21]
	global_load_dwordx4 v[124:127], v[148:149], off
	global_load_dwordx4 v[128:131], v[148:149], off offset:1024
	v_lshl_add_u64 v[148:149], v[148:149], 0, s[20:21]
	global_load_dwordx4 v[132:135], v[148:149], off
	global_load_dwordx4 v[136:139], v[148:149], off offset:1024
	global_load_dwordx4 v[140:143], v[154:155], off
	global_load_dwordx4 v[144:147], v[154:155], off offset:1024
	s_waitcnt vmcnt(0)
; __device__ __forceinline__ void load_row(const Params& p, int r, int mode, int lane, f32x4 (&v)[8]) {
;     ...
;         const float* P = (const float*)(p.ws + WS_PART) + (size_t)(r - TP) * DM;
; #pragma unroll
;         for (int j = 0; j < 8; ++j) {
;             f32x4 a = (f32x4){0.f, 0.f, 0.f, 0.f};
; #pragma unroll
;             for (int q = 0; q < 8; ++q) a += ((const f32x4*)(P + (size_t)q * 512 * DM))[j * 64 + lane];
;             v[j] = ((const f32x4*)base)[j * 64 + lane] + alpha * a;
;             if (mode < 2) ((f32x4*)(X + (size_t)r * DM))[j * 64 + lane] = v[j];
;         }
	v_pk_add_f32 v[78:79], v[78:79], 0 op_sel_hi:[1,0]
	v_pk_add_f32 v[76:77], v[76:77], 0 op_sel_hi:[1,0]
	v_pk_add_f32 v[78:79], v[78:79], v[86:87]
	v_pk_add_f32 v[76:77], v[76:77], v[84:85]
	v_pk_add_f32 v[78:79], v[78:79], v[94:95]
	v_pk_add_f32 v[76:77], v[76:77], v[92:93]
	v_pk_add_f32 v[78:79], v[78:79], v[102:103]
	v_pk_add_f32 v[76:77], v[76:77], v[100:101]
	v_pk_add_f32 v[78:79], v[78:79], v[110:111]
	v_pk_add_f32 v[76:77], v[76:77], v[108:109]
	v_pk_add_f32 v[78:79], v[78:79], v[118:119]
	v_pk_add_f32 v[76:77], v[76:77], v[116:117]
	v_pk_add_f32 v[78:79], v[78:79], v[126:127]
	v_pk_add_f32 v[76:77], v[76:77], v[124:125]
	v_pk_add_f32 v[78:79], v[78:79], v[134:135]
	v_pk_add_f32 v[76:77], v[76:77], v[132:133]
	v_pk_add_f32 v[20:21], v[142:143], v[78:79]
	v_pk_add_f32 v[18:19], v[140:141], v[76:77]
	global_store_dwordx4 v[154:155], v[18:21], off
	v_pk_add_f32 v[82:83], v[82:83], 0 op_sel_hi:[1,0]
	v_pk_add_f32 v[80:81], v[80:81], 0 op_sel_hi:[1,0]
	v_pk_add_f32 v[82:83], v[82:83], v[90:91]
	v_pk_add_f32 v[80:81], v[80:81], v[88:89]
	v_pk_add_f32 v[82:83], v[82:83], v[98:99]
	v_pk_add_f32 v[80:81], v[80:81], v[96:97]
	v_pk_add_f32 v[82:83], v[82:83], v[106:107]
	v_pk_add_f32 v[80:81], v[80:81], v[104:105]
	v_pk_add_f32 v[82:83], v[82:83], v[114:115]
	v_pk_add_f32 v[80:81], v[80:81], v[112:113]
	v_pk_add_f32 v[82:83], v[82:83], v[122:123]
	v_pk_add_f32 v[80:81], v[80:81], v[120:121]
	v_pk_add_f32 v[82:83], v[82:83], v[130:131]
	v_pk_add_f32 v[80:81], v[80:81], v[128:129]
	v_pk_add_f32 v[82:83], v[82:83], v[138:139]
	v_pk_add_f32 v[80:81], v[80:81], v[136:137]
	v_pk_add_f32 v[24:25], v[146:147], v[82:83]
	v_pk_add_f32 v[22:23], v[144:145], v[80:81]
	global_store_dwordx4 v[154:155], v[22:25], off offset:1024
	v_lshl_add_u64 v[148:149], v[152:153], 0, s[22:23]
	v_lshl_add_u64 v[154:155], v[150:151], 0, s[22:23]
	global_load_dwordx4 v[76:79], v[148:149], off offset:2048
	global_load_dwordx4 v[80:83], v[148:149], off offset:3072
	v_lshl_add_u64 v[148:149], v[148:149], 0, s[20:21]
	global_load_dwordx4 v[84:87], v[148:149], off offset:2048
	global_load_dwordx4 v[88:91], v[148:149], off offset:3072
	v_lshl_add_u64 v[148:149], v[148:149], 0, s[20:21]
	global_load_dwordx4 v[92:95], v[148:149], off offset:2048
	global_load_dwordx4 v[96:99], v[148:149], off offset:3072
	v_lshl_add_u64 v[148:149], v[148:149], 0, s[20:21]
	global_load_dwordx4 v[100:103], v[148:149], off offset:2048
	global_load_dwordx4 v[104:107], v[148:149], off offset:3072
	v_lshl_add_u64 v[148:149], v[148:149], 0, s[20:21]
	global_load_dwordx4 v[108:111], v[148:149], off offset:2048
	global_load_dwordx4 v[112:115], v[148:149], off offset:3072
	v_lshl_add_u64 v[148:149], v[148:149], 0, s[20:21]
	global_load_dwordx4 v[116:119], v[148:149], off offset:2048
	global_load_dwordx4 v[120:123], v[148:149], off offset:3072
	v_lshl_add_u64 v[148:149], v[148:149], 0, s[20:21]
	global_load_dwordx4 v[124:127], v[148:149], off offset:2048
	global_load_dwordx4 v[128:131], v[148:149], off offset:3072
	v_lshl_add_u64 v[148:149], v[148:149], 0, s[20:21]
	global_load_dwordx4 v[132:135], v[148:149], off offset:2048
	global_load_dwordx4 v[136:139], v[148:149], off offset:3072
	global_load_dwordx4 v[140:143], v[154:155], off offset:2048
	global_load_dwordx4 v[144:147], v[154:155], off offset:3072
	s_waitcnt vmcnt(0)
	v_pk_add_f32 v[78:79], v[78:79], 0 op_sel_hi:[1,0]
	v_pk_add_f32 v[76:77], v[76:77], 0 op_sel_hi:[1,0]
	v_pk_add_f32 v[78:79], v[78:79], v[86:87]
	v_pk_add_f32 v[76:77], v[76:77], v[84:85]
	v_pk_add_f32 v[78:79], v[78:79], v[94:95]
	v_pk_add_f32 v[76:77], v[76:77], v[92:93]
	v_pk_add_f32 v[78:79], v[78:79], v[102:103]
	v_pk_add_f32 v[76:77], v[76:77], v[100:101]
	v_pk_add_f32 v[78:79], v[78:79], v[110:111]
	v_pk_add_f32 v[76:77], v[76:77], v[108:109]
	v_pk_add_f32 v[78:79], v[78:79], v[118:119]
	v_pk_add_f32 v[76:77], v[76:77], v[116:117]
	v_pk_add_f32 v[78:79], v[78:79], v[126:127]
	v_pk_add_f32 v[76:77], v[76:77], v[124:125]
	v_pk_add_f32 v[78:79], v[78:79], v[134:135]
	v_pk_add_f32 v[76:77], v[76:77], v[132:133]
	v_pk_add_f32 v[28:29], v[142:143], v[78:79]
	v_pk_add_f32 v[26:27], v[140:141], v[76:77]
	global_store_dwordx4 v[154:155], v[26:29], off offset:2048
	v_pk_add_f32 v[82:83], v[82:83], 0 op_sel_hi:[1,0]
	v_pk_add_f32 v[80:81], v[80:81], 0 op_sel_hi:[1,0]
	v_pk_add_f32 v[82:83], v[82:83], v[90:91]
	v_pk_add_f32 v[80:81], v[80:81], v[88:89]
	v_pk_add_f32 v[82:83], v[82:83], v[98:99]
	v_pk_add_f32 v[80:81], v[80:81], v[96:97]
	v_pk_add_f32 v[82:83], v[82:83], v[106:107]
	v_pk_add_f32 v[80:81], v[80:81], v[104:105]
	v_pk_add_f32 v[82:83], v[82:83], v[114:115]
	v_pk_add_f32 v[80:81], v[80:81], v[112:113]
	v_pk_add_f32 v[82:83], v[82:83], v[122:123]
	v_pk_add_f32 v[80:81], v[80:81], v[120:121]
	v_pk_add_f32 v[82:83], v[82:83], v[130:131]
	v_pk_add_f32 v[80:81], v[80:81], v[128:129]
	v_pk_add_f32 v[82:83], v[82:83], v[138:139]
	v_pk_add_f32 v[80:81], v[80:81], v[136:137]
	v_pk_add_f32 v[32:33], v[146:147], v[82:83]
	v_pk_add_f32 v[30:31], v[144:145], v[80:81]
	global_store_dwordx4 v[154:155], v[30:33], off offset:3072
	v_mov_b64_e32 v[60:61], v[0:1]

; #define MFMA16(a, b, c) __builtin_amdgcn_mfma_f32_16x16x32_bf16((a), (b), (c), 0, 0, 0)
; template <int MODE>
; __device__ __forceinline__ void attn_item(const Params& p, unsigned char* sm, int h, int tok0, int nrows, int kvt0, int ntiles, int nkeys, int qpos0, const int TIDX) {
;     ...
;         const unsigned char* Kb = sm + (t & 1) * 35840; const unsigned char* Vb = Kb + 17408;
;         f32x4 s[4];
; #pragma unroll
;         for (int kb = 0; kb < 4; ++kb) {
;             f32x4 acc = (f32x4){0.f, 0.f, 0.f, 0.f};
; #pragma unroll
;             for (int ks = 0; ks < KS; ++ks) {
;                 const bf16x8 A = *(const bf16x8*)(Kb + (16 * kb + r16) * 272 + (doff + 32 * ks + 8 * g) * 2);
;                 acc = MFMA16(A, Qf[ks], acc);
;             }
;             s[kb] = acc;
;         }
;         float mx = -1e30f;
;         if ((MODE == 1 || (64 * t + 63 - qpos0 <= -128)) && 64 * (t + 1) <= nkeys) {
;             const float bfar = MODE == 0 ? BIAS[0] : 0.f;
; #pragma unroll
;             for (int kb = 0; kb < 4; ++kb)
; #pragma unroll
;                 for (int j = 0; j < 4; ++j) { const float v = s[kb][j] * SC + bfar; s[kb][j] = v; mx = fmaxf(mx, v); }
;     ...
;                 const u32x2 a0 = *(const u32x2*)(Vb + (16 * cb + r16) * 144 + (32 * k2 + 4 * g) * 2);
;                 const u32x2 a1 = *(const u32x2*)(Vb + (16 * cb + r16) * 144 + (32 * k2 + 16 + 4 * g) * 2);
;                 const bf16x8 A = __builtin_bit_cast(bf16x8, ((u32x4){a0.x, a0.y, a1.x, a1.y}));
.LBB0_97:
	s_bitcmp1_b32 s14, 0
	s_cselect_b32 s14, 0x8c00, 0
	s_add_i32 s24, s14, 0
	v_add3_u32 v62, s24, v107, v106
	v_add3_u32 v63, s24, v108, v106
	v_add3_u32 v64, s24, v109, v106
	v_add3_u32 v80, s24, v110, v106
	v_add3_u32 v212, s24, v74, v111
	ds_read_b128 v[120:123], v62
	ds_read_b128 v[124:127], v62 offset:64
	ds_read_b128 v[128:131], v63
	ds_read_b128 v[132:135], v63 offset:64
	ds_read_b128 v[136:139], v64
	ds_read_b128 v[140:143], v64 offset:64
	ds_read_b128 v[144:147], v80
	ds_read_b128 v[148:151], v80 offset:64
	v_add_u32_e32 v213, 0x4000, v212
	ds_read_b64 v[152:153], v213 offset:1024
	ds_read_b64 v[154:155], v213 offset:1056
	v_add_u32_e32 v213, 0x4000, v212
	ds_read_b64 v[156:157], v213 offset:1088
	ds_read_b64 v[158:159], v213 offset:1120
	v_add_u32_e32 v213, 0x4800, v212
	ds_read_b64 v[160:161], v213 offset:1280
	ds_read_b64 v[162:163], v213 offset:1312
	s_add_i32 s14, s19, s22
	s_sub_i32 s14, s14, 64
	s_cmpk_gt_i32 s14, 0xff41
	s_cselect_b64 s[14:15], -1, 0
	s_cmp_gt_i32 s22, s17
	s_cselect_b64 s[26:27], -1, 0
	s_or_b64 s[26:27], s[14:15], s[26:27]
	s_mov_b64 s[14:15], -1
	s_andn2_b64 vcc, exec, s[26:27]
	s_waitcnt lgkmcnt(12)
	v_mfma_f32_16x16x32_bf16 v[66:69], v[120:123], v[34:37], 0
	v_mfma_f32_16x16x32_bf16 v[66:69], v[124:127], v[38:41], v[66:69]
	v_add_u32_e32 v213, 0x4800, v212
	ds_read_b64 v[164:165], v213 offset:1344
	ds_read_b64 v[166:167], v213 offset:1376
	s_waitcnt lgkmcnt(12)
	v_mfma_f32_16x16x32_bf16 v[70:73], v[128:131], v[34:37], 0
	v_mfma_f32_16x16x32_bf16 v[70:73], v[132:135], v[38:41], v[70:73]
	v_add_u32_e32 v213, 0x5000, v212
	ds_read_b64 v[204:205], v213 offset:1536
	ds_read_b64 v[206:207], v213 offset:1568
	s_waitcnt lgkmcnt(12)
	v_mfma_f32_16x16x32_bf16 v[58:61], v[136:139], v[34:37], 0
	v_mfma_f32_16x16x32_bf16 v[58:61], v[140:143], v[38:41], v[58:61]
	v_add_u32_e32 v213, 0x5000, v212
	ds_read_b64 v[208:209], v213 offset:1600
	ds_read_b64 v[210:211], v213 offset:1632
	s_waitcnt lgkmcnt(12)
	v_mfma_f32_16x16x32_bf16 v[62:65], v[144:147], v[34:37], 0
	v_mfma_f32_16x16x32_bf16 v[62:65], v[148:151], v[38:41], v[62:65]
	s_nop 1
	v_mul_f32_e32 v66, 0x3e38aa3b, v66
	v_mul_f32_e32 v67, 0x3e38aa3b, v67
	s_cbranch_vccz .LBB0_99
	s_add_i32 s14, 0, 0x11800
	v_mov_b32_e32 v80, s14
	ds_read_b32 v94, v80
	s_mov_b32 s26, 0x3e38aa3b
	s_mov_b32 s14, 0xf149f2ca
	s_waitcnt lgkmcnt(0)
	v_pk_add_f32 v[84:85], v[66:67], v[94:95] op_sel_hi:[1,0]
	v_pk_fma_f32 v[86:87], v[68:69], s[26:27], v[94:95] op_sel_hi:[1,0,0]
	v_max3_f32 v90, v84, s14, v85
	v_pk_fma_f32 v[80:81], v[70:71], s[26:27], v[94:95] op_sel_hi:[1,0,0]
	v_max3_f32 v90, v90, v86, v87
	v_pk_fma_f32 v[82:83], v[72:73], s[26:27], v[94:95] op_sel_hi:[1,0,0]
	v_max3_f32 v90, v90, v80, v81
	v_pk_fma_f32 v[88:89], v[58:59], s[26:27], v[94:95] op_sel_hi:[1,0,0]
	v_max3_f32 v90, v90, v82, v83
	v_max3_f32 v92, v90, v88, v89
	v_pk_fma_f32 v[90:91], v[60:61], s[26:27], v[94:95] op_sel_hi:[1,0,0]
	s_mov_b64 s[14:15], 0
	v_max3_f32 v95, v92, v90, v91
	v_pk_fma_f32 v[92:93], v[62:63], s[26:27], v[94:95] op_sel_hi:[1,0,0]
	s_nop 0
	v_max3_f32 v115, v95, v92, v93
	v_pk_fma_f32 v[94:95], v[64:65], s[26:27], v[94:95] op_sel_hi:[1,0,0]
	s_nop 0
	v_max3_f32 v115, v115, v94, v95

; __device__ __forceinline__ unsigned pk2(float lo, float hi) { unsigned r; asm("v_cvt_pk_bf16_f32 %0, %1, %2" : "=v"(r) : "v"(lo), "v"(hi)); return r; }
; #define BAR_LDS() do { asm volatile("s_waitcnt lgkmcnt(0)" ::: "memory"); __builtin_amdgcn_s_barrier(); asm volatile("" ::: "memory"); } while (0)
; #define MFMA16(a, b, c) __builtin_amdgcn_mfma_f32_16x16x32_bf16((a), (b), (c), 0, 0, 0)
; #define AT_STORE(buf) do { unsigned char* b_ = sm + (buf) * 35840; _Pragma("unroll") for (int k_ = 0; k_ < 2; ++k_) { const int id_ = tid + 512 * k_; \
;         *(u32x4*)(b_ + (id_ >> 4) * 272 + (id_ & 15) * 16) = pkk[k_]; *(u32x4*)(b_ + 17408 + (id_ >> 3) * 144 + (id_ & 7) * 16) = pvv[k_]; } } while (0)
; template <int MODE>
; __device__ __forceinline__ void attn_item(const Params& p, unsigned char* sm, int h, int tok0, int nrows, int kvt0, int ntiles, int nkeys, int qpos0, const int TIDX) {
;     ...
;         mx = fmaxf(mx, __shfl_xor(mx, 16)); mx = fmaxf(mx, __shfl_xor(mx, 32));
;         const float mnew = fmaxf(m_run, mx), alpha = __builtin_amdgcn_exp2f(m_run - mnew); m_run = mnew;
;         float psum = 0.f;
; #pragma unroll
;         for (int kb = 0; kb < 4; ++kb)
; #pragma unroll
;             for (int j = 0; j < 4; ++j) { const float pv_ = __builtin_amdgcn_exp2f(s[kb][j] - mnew); s[kb][j] = pv_; psum += pv_; }
;         l_run = l_run * alpha + psum;
; #pragma unroll
;         for (int cb = 0; cb < 8; ++cb) O[cb] = O[cb] * alpha;
;         bf16x8 Pf[2];
; #pragma unroll
;         for (int k2 = 0; k2 < 2; ++k2) { u32x4 tt; tt.x = pk2(s[2 * k2][0], s[2 * k2][1]); tt.y = pk2(s[2 * k2][2], s[2 * k2][3]); tt.z = pk2(s[2 * k2 + 1][0], s[2 * k2 + 1][1]); tt.w = pk2(s[2 * k2 + 1][2], s[2 * k2 + 1][3]);
;             Pf[k2] = __builtin_bit_cast(bf16x8, tt); }
; #pragma unroll
;         for (int cb = 0; cb < 8; ++cb)
; #pragma unroll
;             for (int k2 = 0; k2 < 2; ++k2) {
;                 const u32x2 a0 = *(const u32x2*)(Vb + (16 * cb + r16) * 144 + (32 * k2 + 4 * g) * 2);
;                 const u32x2 a1 = *(const u32x2*)(Vb + (16 * cb + r16) * 144 + (32 * k2 + 16 + 4 * g) * 2);
;                 const bf16x8 A = __builtin_bit_cast(bf16x8, ((u32x4){a0.x, a0.y, a1.x, a1.y}));
;                 O[cb] = MFMA16(A, Pf[k2], O[cb]);
;             }
;         if (t + 1 < ntiles) AT_STORE((t + 1) & 1);
;         BAR_LDS();
.LBB0_101:
	ds_bpermute_b32 v58, v186, v115
	v_max_f32_e32 v59, v115, v115
	s_andn2_b64 vcc, exec, s[12:13]
	s_waitcnt lgkmcnt(0)
	v_max_f32_e32 v58, v58, v58
	v_max_f32_e32 v58, v59, v58
	ds_bpermute_b32 v59, v187, v58
	s_waitcnt lgkmcnt(0)
	v_max3_f32 v67, v114, v58, v59
	v_sub_f32_e32 v58, v114, v67
	v_exp_f32_e32 v66, v58
	v_sub_f32_e32 v58, v84, v67
	v_exp_f32_e32 v68, v58
	v_sub_f32_e32 v58, v85, v67
	v_exp_f32_e32 v69, v58
	v_sub_f32_e32 v58, v86, v67
	v_exp_f32_e32 v70, v58
	v_sub_f32_e32 v58, v87, v67
	v_exp_f32_e32 v71, v58
	v_sub_f32_e32 v58, v80, v67
	v_exp_f32_e32 v72, v58
	v_sub_f32_e32 v58, v81, v67
	v_exp_f32_e32 v73, v58
	v_sub_f32_e32 v58, v82, v67
	v_exp_f32_e32 v80, v58
	v_sub_f32_e32 v58, v83, v67
	v_exp_f32_e32 v81, v58
	v_sub_f32_e32 v58, v88, v67
	v_exp_f32_e32 v82, v58
	v_sub_f32_e32 v58, v89, v67
	v_exp_f32_e32 v83, v58
	v_sub_f32_e32 v58, v90, v67
	v_exp_f32_e32 v84, v58
	v_sub_f32_e32 v58, v91, v67
	v_exp_f32_e32 v85, v58
	v_sub_f32_e32 v58, v92, v67
	v_exp_f32_e32 v86, v58
	v_sub_f32_e32 v58, v93, v67
	v_exp_f32_e32 v87, v58
	v_sub_f32_e32 v58, v94, v67
	v_exp_f32_e32 v88, v58
	v_sub_f32_e32 v58, v95, v67
	v_pk_mul_f32 v[32:33], v[32:33], v[66:67] op_sel_hi:[1,0]
	v_pk_mul_f32 v[30:31], v[30:31], v[66:67] op_sel_hi:[1,0]
	v_cvt_pk_bf16_f32 v62, v68, v69
	v_cvt_pk_bf16_f32 v63, v70, v71
	v_cvt_pk_bf16_f32 v64, v72, v73
	v_cvt_pk_bf16_f32 v65, v80, v81
	v_exp_f32_e32 v89, v58
	s_nop 0
	v_mfma_f32_16x16x32_bf16 v[30:33], v[152:155], v[62:65], v[30:33]
	v_add_u32_e32 v213, 0x5800, v212
	ds_read_b64 v[152:153], v213 offset:1792
	ds_read_b64 v[154:155], v213 offset:1824
	v_pk_mul_f32 v[60:61], v[4:5], v[66:67] op_sel_hi:[1,0]
	v_pk_mul_f32 v[58:59], v[2:3], v[66:67] op_sel_hi:[1,0]
	v_cvt_pk_bf16_f32 v2, v82, v83
	v_cvt_pk_bf16_f32 v3, v84, v85
	v_cvt_pk_bf16_f32 v4, v86, v87
	v_cvt_pk_bf16_f32 v5, v88, v89
	v_pk_mul_f32 v[24:25], v[24:25], v[66:67] op_sel_hi:[1,0]
	s_nop 0
	v_mfma_f32_16x16x32_bf16 v[30:33], v[156:159], v[2:5], v[30:33]
	v_add_u32_e32 v213, 0x5800, v212
	ds_read_b64 v[156:157], v213 offset:1856
	ds_read_b64 v[158:159], v213 offset:1888
	v_pk_mul_f32 v[22:23], v[22:23], v[66:67] op_sel_hi:[1,0]
	v_pk_mul_f32 v[28:29], v[28:29], v[66:67] op_sel_hi:[1,0]
	v_pk_mul_f32 v[26:27], v[26:27], v[66:67] op_sel_hi:[1,0]
	v_mfma_f32_16x16x32_bf16 v[22:25], v[160:163], v[62:65], v[22:25]
	v_add_u32_e32 v213, 0x6800, v212
	ds_read_b64 v[160:161], v213 offset:0
	ds_read_b64 v[162:163], v213 offset:32
	v_pk_mul_f32 v[16:17], v[16:17], v[66:67] op_sel_hi:[1,0]
	v_mfma_f32_16x16x32_bf16 v[22:25], v[164:167], v[2:5], v[22:25]
	v_add_u32_e32 v213, 0x6800, v212
	ds_read_b64 v[164:165], v213 offset:64
	ds_read_b64 v[166:167], v213 offset:96
	v_pk_mul_f32 v[14:15], v[14:15], v[66:67] op_sel_hi:[1,0]
	v_pk_mul_f32 v[20:21], v[20:21], v[66:67] op_sel_hi:[1,0]
	v_mfma_f32_16x16x32_bf16 v[26:29], v[204:207], v[62:65], v[26:29]
	v_add_u32_e32 v213, 0x7000, v212
	ds_read_b64 v[204:205], v213 offset:256
	ds_read_b64 v[206:207], v213 offset:288
	v_pk_mul_f32 v[18:19], v[18:19], v[66:67] op_sel_hi:[1,0]
	v_mfma_f32_16x16x32_bf16 v[26:29], v[208:211], v[2:5], v[26:29]
	v_add_u32_e32 v213, 0x7000, v212
	ds_read_b64 v[208:209], v213 offset:320
	ds_read_b64 v[210:211], v213 offset:352
	v_pk_mul_f32 v[8:9], v[8:9], v[66:67] op_sel_hi:[1,0]
	v_pk_mul_f32 v[6:7], v[6:7], v[66:67] op_sel_hi:[1,0]
	s_waitcnt lgkmcnt(10)
	v_mfma_f32_16x16x32_bf16 v[14:17], v[152:155], v[62:65], v[14:17]
	v_add_u32_e32 v213, 0x7800, v212
	ds_read_b64 v[152:153], v213 offset:512
	ds_read_b64 v[154:155], v213 offset:544
	v_pk_mul_f32 v[12:13], v[12:13], v[66:67] op_sel_hi:[1,0]
	s_waitcnt lgkmcnt(10)
	v_mfma_f32_16x16x32_bf16 v[14:17], v[156:159], v[2:5], v[14:17]
	v_add_u32_e32 v213, 0x7800, v212
	ds_read_b64 v[156:157], v213 offset:576
	ds_read_b64 v[158:159], v213 offset:608
	v_pk_mul_f32 v[10:11], v[10:11], v[66:67] op_sel_hi:[1,0]
	s_waitcnt lgkmcnt(10)
	v_mfma_f32_16x16x32_bf16 v[18:21], v[160:163], v[62:65], v[18:21]
	v_add_u32_e32 v213, 0x8000, v212
	ds_read_b64 v[160:161], v213 offset:768
	ds_read_b64 v[162:163], v213 offset:800
	s_waitcnt lgkmcnt(10)
	v_mfma_f32_16x16x32_bf16 v[18:21], v[164:167], v[2:5], v[18:21]
	v_add_u32_e32 v213, 0x8000, v212
	ds_read_b64 v[164:165], v213 offset:832
	ds_read_b64 v[166:167], v213 offset:864
	s_waitcnt lgkmcnt(10)
	v_mfma_f32_16x16x32_bf16 v[6:9], v[204:207], v[62:65], v[6:9]
	s_waitcnt lgkmcnt(8)
	v_mfma_f32_16x16x32_bf16 v[6:9], v[208:211], v[2:5], v[6:9]
	s_waitcnt lgkmcnt(6)
	v_mfma_f32_16x16x32_bf16 v[10:13], v[152:155], v[62:65], v[10:13]
	s_waitcnt lgkmcnt(4)
	v_mfma_f32_16x16x32_bf16 v[10:13], v[156:159], v[2:5], v[10:13]
	s_waitcnt lgkmcnt(2)
	v_mfma_f32_16x16x32_bf16 v[58:61], v[160:163], v[62:65], v[58:61]
	s_waitcnt lgkmcnt(0)
	v_mfma_f32_16x16x32_bf16 v[2:5], v[164:167], v[2:5], v[58:61]
	s_cbranch_vccnz .LBB0_103
	s_bitcmp1_b32 s23, 0
	s_cselect_b32 s12, 0x8c00, 0
	s_add_i32 s12, s12, 0
	s_nop 0
	v_add_u32_e32 v58, s12, v98
	v_add_u32_e32 v59, v58, v100
	v_add_u32_e32 v60, s12, v99
	v_add_u32_e32 v61, v60, v101
	v_add_u32_e32 v58, v58, v102
	v_add_u32_e32 v60, v60, v103
	s_waitcnt vmcnt(3)
	ds_write_b128 v59, v[42:45]
	s_waitcnt vmcnt(2)
	ds_write_b128 v61, v[46:49] offset:17408
	s_waitcnt vmcnt(1)
	ds_write_b128 v58, v[50:53]
	s_waitcnt vmcnt(0)
	ds_write_b128 v60, v[54:57] offset:17408

; #define BAR_LDS() do { asm volatile("s_waitcnt lgkmcnt(0)" ::: "memory"); __builtin_amdgcn_s_barrier(); asm volatile("" ::: "memory"); } while (0)
; __device__ __forceinline__ void gla_item(const Params& p, unsigned char* sm, int h, int job0, int jobstride, int nchunks, int tok0, int nvalid, const float* s_init, float* s_out, const int TIDX) {
;     ...
;     for (int ci = 0; ci < nchunks; ++ci) {
;         const int t0 = tok0 + ci * 64;
;     ...
;         BAR_LDS();
;         if (ci + 1 < nchunks) { GLA_STORE(); }
;         BAR_LDS();
;     }
.Lgla_next:
	s_add_i32 s96, s96, 4
	s_add_i32 s81, s81, 64
	s_add_i32 s91, s91, 1
	s_cmp_lg_u32 s84, s81
	s_cbranch_scc0 .LBB0_176

; __device__ __forceinline__ unsigned pk2(float lo, float hi) { unsigned r; asm("v_cvt_pk_bf16_f32 %0, %1, %2" : "=v"(r) : "v"(lo), "v"(hi)); return r; }
; __device__ __forceinline__ void gla_item(const Params& p, unsigned char* sm, int h, int job0, int jobstride, int nchunks, int tok0, int nvalid, const float* s_init, float* s_out, const int TIDX) {
;     ...
; #pragma unroll
;         for (int ib = 0; ib < 4; ++ib)
; #pragma unroll
;             for (int j = 0; j < 4; ++j) {
;                 const int i = 16 * ib + 4 * g + j; const float rs = RSl[i];
;                 *(bf16_t*)(OTl + i * 528 + (32 * w + r16) * 2) = (bf16_t)(pk2(o[ib][0][j] * rs, 0.f) & 0xffffu);
;                 *(bf16_t*)(OTl + i * 528 + (32 * w + 16 + r16) * 2) = (bf16_t)(pk2(o[ib][1][j] * rs, 0.f) & 0xffffu);
;             }
.LBB0_165:
	s_or_b64 exec, exec, s[38:39]
	s_waitcnt lgkmcnt(0)
	s_barrier
	ds_read_b128 v[238:241], v214
	ds_read_b128 v[242:245], v214 offset:64
	ds_read_b128 v[246:249], v214 offset:128
	ds_read_b128 v[250:253], v214 offset:192
	s_waitcnt lgkmcnt(0)
	v_mul_f32_e32 v152, v152, v238
	v_mul_f32_e32 v156, v156, v238
	v_mul_f32_e32 v153, v153, v239
	v_mul_f32_e32 v157, v157, v239
	v_mul_f32_e32 v154, v154, v240
	v_mul_f32_e32 v158, v158, v240
	v_mul_f32_e32 v155, v155, v241
	v_mul_f32_e32 v159, v159, v241
	v_cvt_pk_bf16_f32 v152, v152, v1
	v_cvt_pk_bf16_f32 v156, v156, v1
	v_cvt_pk_bf16_f32 v153, v153, v1
	v_cvt_pk_bf16_f32 v157, v157, v1
	v_cvt_pk_bf16_f32 v154, v154, v1
	v_cvt_pk_bf16_f32 v158, v158, v1
	v_cvt_pk_bf16_f32 v155, v155, v1
	v_cvt_pk_bf16_f32 v159, v159, v1
	ds_write_b16 v231, v152 offset:32
	ds_write_b16 v231, v156
	ds_write_b16 v232, v153 offset:32
	ds_write_b16 v232, v157
	ds_write_b16 v232, v154 offset:560
	ds_write_b16 v232, v158 offset:528
	ds_write_b16 v232, v155 offset:1088
	ds_write_b16 v232, v159 offset:1056
	v_mul_f32_e32 v144, v144, v242
	v_mul_f32_e32 v148, v148, v242
	v_mul_f32_e32 v145, v145, v243
	v_mul_f32_e32 v149, v149, v243
	v_mul_f32_e32 v146, v146, v244
	v_mul_f32_e32 v150, v150, v244
	v_mul_f32_e32 v147, v147, v245
	v_mul_f32_e32 v151, v151, v245
	v_cvt_pk_bf16_f32 v144, v144, v1
	v_cvt_pk_bf16_f32 v148, v148, v1
	v_cvt_pk_bf16_f32 v145, v145, v1
	v_cvt_pk_bf16_f32 v149, v149, v1
	v_cvt_pk_bf16_f32 v146, v146, v1
	v_cvt_pk_bf16_f32 v150, v150, v1
	v_cvt_pk_bf16_f32 v147, v147, v1
	v_cvt_pk_bf16_f32 v151, v151, v1
	ds_write_b16 v232, v144 offset:7952
	ds_write_b16 v232, v148 offset:7920
	ds_write_b16 v232, v145 offset:8480
	ds_write_b16 v232, v149 offset:8448
	ds_write_b16 v232, v146 offset:9008
	ds_write_b16 v232, v150 offset:8976
	ds_write_b16 v232, v147 offset:9536
	ds_write_b16 v232, v151 offset:9504
	v_mul_f32_e32 v136, v136, v246
	v_mul_f32_e32 v140, v140, v246
	v_mul_f32_e32 v137, v137, v247
	v_mul_f32_e32 v141, v141, v247
	v_mul_f32_e32 v138, v138, v248
	v_mul_f32_e32 v142, v142, v248
	v_mul_f32_e32 v139, v139, v249
	v_mul_f32_e32 v143, v143, v249
	v_cvt_pk_bf16_f32 v136, v136, v1
	v_cvt_pk_bf16_f32 v140, v140, v1
	v_cvt_pk_bf16_f32 v137, v137, v1
	v_cvt_pk_bf16_f32 v141, v141, v1
	v_cvt_pk_bf16_f32 v138, v138, v1
	v_cvt_pk_bf16_f32 v142, v142, v1
	v_cvt_pk_bf16_f32 v139, v139, v1
	v_cvt_pk_bf16_f32 v143, v143, v1
	ds_write_b16 v232, v136 offset:16400
	ds_write_b16 v232, v140 offset:16368
	ds_write_b16 v232, v137 offset:16928
	ds_write_b16 v232, v141 offset:16896
	ds_write_b16 v232, v138 offset:17456
	ds_write_b16 v232, v142 offset:17424
	ds_write_b16 v232, v139 offset:17984
	ds_write_b16 v232, v143 offset:17952
	v_mul_f32_e32 v128, v128, v250
	v_mul_f32_e32 v132, v132, v250
	v_mul_f32_e32 v129, v129, v251
	v_mul_f32_e32 v133, v133, v251
	v_mul_f32_e32 v130, v130, v252
	v_mul_f32_e32 v134, v134, v252
	v_mul_f32_e32 v131, v131, v253
	v_mul_f32_e32 v135, v135, v253
	v_cvt_pk_bf16_f32 v128, v128, v1
	v_cvt_pk_bf16_f32 v132, v132, v1
	v_cvt_pk_bf16_f32 v129, v129, v1
	v_cvt_pk_bf16_f32 v133, v133, v1
	v_cvt_pk_bf16_f32 v130, v130, v1
	v_cvt_pk_bf16_f32 v134, v134, v1
	v_cvt_pk_bf16_f32 v131, v131, v1
	v_cvt_pk_bf16_f32 v135, v135, v1
	ds_write_b16 v232, v128 offset:24848
	ds_write_b16 v232, v132 offset:24816
	ds_write_b16 v232, v129 offset:25376
	ds_write_b16 v232, v133 offset:25344
	ds_write_b16 v232, v130 offset:25904
	ds_write_b16 v232, v134 offset:25872
	ds_write_b16 v232, v131 offset:26432
	ds_write_b16 v232, v135 offset:26400
	s_and_b64 vcc, exec, s[98:99]
	s_cbranch_vccz .Lgla_nostore
	s_waitcnt vmcnt(4)
	ds_write_b128 v171, v[68:71]
	ds_write_b128 v171, v[72:75] offset:17408
	ds_write_b128 v173, v[76:79] offset:34816
	ds_write_b128 v204, v[80:83]
	ds_write_b128 v204, v[84:87] offset:17408
	ds_write_b128 v205, v[88:91] offset:34816
	ds_write_b128 v173, v[92:95] offset:53248
	ds_write_b128 v205, v[96:99] offset:53248
	ds_write_b128 v206, v[100:103] offset:53248
	ds_write_b128 v207, v[104:107] offset:53248
	s_and_saveexec_b64 s[38:39], s[6:7]
	ds_write_b128 v208, v[108:111]
	s_or_b64 exec, exec, s[38:39]
; __device__ __forceinline__ unsigned pk2(float lo, float hi) { unsigned r; asm("v_cvt_pk_bf16_f32 %0, %1, %2" : "=v"(r) : "v"(lo), "v"(hi)); return r; }
; __device__ __forceinline__ float bflo(unsigned u) { return __uint_as_float(u << 16); }
; __device__ __forceinline__ float bfhi(unsigned u) { return __uint_as_float(u & 0xffff0000u); }
; __device__ __forceinline__ float silu_f(float x) { return x * __builtin_amdgcn_rcpf(1.0f + __expf(-x)); }
; #define BAR_LDS() do { asm volatile("s_waitcnt lgkmcnt(0)" ::: "memory"); __builtin_amdgcn_s_barrier(); asm volatile("" ::: "memory"); } while (0)
; __device__ __forceinline__ void gla_item(const Params& p, unsigned char* sm, int h, int job0, int jobstride, int nchunks, int tok0, int nvalid, const float* s_init, float* s_out, const int TIDX) {
;     ...
;         BAR_LDS();
; #pragma unroll
;         for (int k_ = 0; k_ < 4; ++k_) { const int id_ = tid + 512 * k_, row_ = id_ >> 5, seg_ = id_ & 31;
;             if (row_ < nvalid) {
;                 const u32x4 ov = *(const u32x4*)(OTl + row_ * 528 + seg_ * 16);
;                 const f32x4 ga = *(const f32x4*)(GNl + seg_ * 8), gb = *(const f32x4*)(GNl + seg_ * 8 + 4);
;                 const u32x4 gr = grv[k_]; u32x4 wv;
;                 wv.x = pk2(bflo(ov.x) * ga[0] * silu_f(bflo(gr.x)), bfhi(ov.x) * ga[1] * silu_f(bfhi(gr.x)));
;                 wv.y = pk2(bflo(ov.y) * ga[2] * silu_f(bflo(gr.y)), bfhi(ov.y) * ga[3] * silu_f(bfhi(gr.y)));
;                 wv.z = pk2(bflo(ov.z) * gb[0] * silu_f(bflo(gr.z)), bfhi(ov.z) * gb[1] * silu_f(bfhi(gr.z)));
;                 wv.w = pk2(bflo(ov.w) * gb[2] * silu_f(bflo(gr.w)), bfhi(ov.w) * gb[3] * silu_f(bfhi(gr.w)));
;                 *(u32x4*)(CAT + (size_t)(t0 + row_) * DM + h * 256 + seg_ * 8) = wv;
.Lgla_nostore:
	s_waitcnt lgkmcnt(0)
	s_barrier
	s_and_saveexec_b64 vcc, s[28:29]
	s_cbranch_execz .LBB0_169
	s_waitcnt vmcnt(3)
	v_lshlrev_b32_e32 v140, 16, v124
	v_mul_f32_e32 v142, 0xbfb8aa3b, v140
	v_exp_f32_e32 v142, v142
	ds_read_b128 v[132:135], v233
	ds_read_b128 v[136:139], v213
	ds_read_b128 v[128:131], v213 offset:16
	s_waitcnt lgkmcnt(2)
	v_lshlrev_b32_e32 v141, 16, v132
	v_add_f32_e32 v142, 1.0, v142
	v_rcp_f32_e32 v142, v142
	s_waitcnt lgkmcnt(1)
	v_mov_b32_e32 v143, v136
	v_pk_mul_f32 v[140:141], v[142:143], v[140:141]
	s_nop 0
	v_mul_f32_e32 v142, v140, v141
	v_and_b32_e32 v140, 0xffff0000, v124
	v_mul_f32_e32 v124, 0xbfb8aa3b, v140
	v_exp_f32_e32 v124, v124
	v_and_b32_e32 v141, 0xffff0000, v132
	v_add_f32_e32 v124, 1.0, v124
	v_rcp_f32_e32 v136, v124
	s_nop 0
	v_pk_mul_f32 v[136:137], v[136:137], v[140:141]
	s_nop 0
	v_mul_f32_e32 v124, v136, v137
	v_lshlrev_b32_e32 v136, 16, v125
	v_mul_f32_e32 v132, 0xbfb8aa3b, v136
	v_exp_f32_e32 v132, v132
	v_mov_b32_e32 v141, v138
	v_lshlrev_b32_e32 v137, 16, v133
	v_and_b32_e32 v133, 0xffff0000, v133
	v_add_f32_e32 v132, 1.0, v132
	v_rcp_f32_e32 v140, v132
	v_and_b32_e32 v132, 0xffff0000, v125
	v_mul_f32_e32 v125, 0xbfb8aa3b, v132
	v_exp_f32_e32 v125, v125
	v_pk_mul_f32 v[136:137], v[140:141], v[136:137]
	v_cvt_pk_bf16_f32 v124, v142, v124
	v_add_f32_e32 v125, 1.0, v125
	v_rcp_f32_e32 v138, v125
	v_mul_f32_e32 v136, v136, v137
	s_waitcnt lgkmcnt(0)
	v_mov_b32_e32 v137, v128
	v_pk_mul_f32 v[132:133], v[138:139], v[132:133]
	s_nop 0
	v_mul_f32_e32 v125, v132, v133
	v_lshlrev_b32_e32 v132, 16, v126
	v_cvt_pk_bf16_f32 v125, v136, v125
	v_mul_f32_e32 v136, 0xbfb8aa3b, v132
	v_exp_f32_e32 v136, v136
	v_lshlrev_b32_e32 v133, 16, v134
	v_add_f32_e32 v136, 1.0, v136
	v_rcp_f32_e32 v136, v136
	s_nop 0
	v_pk_mul_f32 v[132:133], v[136:137], v[132:133]
	s_nop 0
	v_mul_f32_e32 v136, v132, v133
	v_and_b32_e32 v132, 0xffff0000, v126
	v_mul_f32_e32 v126, 0xbfb8aa3b, v132
	v_exp_f32_e32 v126, v126
	v_and_b32_e32 v133, 0xffff0000, v134
	v_add_f32_e32 v126, 1.0, v126
	v_rcp_f32_e32 v128, v126
	s_nop 0
	v_pk_mul_f32 v[128:129], v[128:129], v[132:133]
	s_nop 0
	v_mul_f32_e32 v126, v128, v129
	v_lshlrev_b32_e32 v128, 16, v127
	v_mul_f32_e32 v132, 0xbfb8aa3b, v128
	v_exp_f32_e32 v132, v132
	v_lshlrev_b32_e32 v129, 16, v135
	v_mov_b32_e32 v133, v130
	v_cvt_pk_bf16_f32 v126, v136, v126
	v_add_f32_e32 v132, 1.0, v132
	v_rcp_f32_e32 v132, v132
	s_nop 0
	v_pk_mul_f32 v[128:129], v[132:133], v[128:129]
	s_nop 0
	v_mul_f32_e32 v132, v128, v129
	v_and_b32_e32 v128, 0xffff0000, v127
	v_mul_f32_e32 v127, 0xbfb8aa3b, v128
	v_exp_f32_e32 v127, v127
	v_and_b32_e32 v129, 0xffff0000, v135
	v_add_f32_e32 v127, 1.0, v127
	v_rcp_f32_e32 v130, v127
	s_nop 0
	v_pk_mul_f32 v[128:129], v[130:131], v[128:129]
	s_nop 0
	v_mul_f32_e32 v127, v128, v129
	v_add_u32_e32 v128, s81, v216
	v_ashrrev_i32_e32 v129, 31, v128
	v_lshlrev_b64 v[128:129], 12, v[128:129]
	v_lshl_add_u64 v[128:129], v[184:185], 0, v[128:129]
	v_cvt_pk_bf16_f32 v127, v132, v127
	global_store_dwordx4 v[128:129], v[124:127], off
	s_or_b64 exec, exec, vcc
	s_and_saveexec_b64 vcc, s[30:31]
	s_cbranch_execnz .LBB0_170

; #define BAR_LDS() do { asm volatile("s_waitcnt lgkmcnt(0)" ::: "memory"); __builtin_amdgcn_s_barrier(); asm volatile("" ::: "memory"); } while (0)
; __device__ __forceinline__ void gla_item(const Params& p, unsigned char* sm, int h, int job0, int jobstride, int nchunks, int tok0, int nvalid, const float* s_init, float* s_out, const int TIDX) {
;     ...
;             }
;         }
;         BAR_LDS();
;         if (ci + 1 < nchunks) { GLA_STORE(); }
;         BAR_LDS();
.LBB0_173:
	s_or_b64 exec, exec, vcc
	s_branch .Lgla_next

; __device__ __forceinline__ void epilogue(const Params& p, int mode, int atomic, float alpha, const f32x4 (&acc)[2][2][4][2], int pm, int pn, int wr, int wc, int fr, int fq) {
;     ...
;     } else if (mode == EPI_RESX || mode == EPI_RESIN) {
;         float* X = p.out;
; #pragma unroll
;         for (int ai = 0; ai < 2; ++ai)
; #pragma unroll
;             for (int m = 0; m < 4; ++m) {
;                 const int row = row0 + ai * 128 + m * 16;
;                 const float* src = (mode == EPI_RESIN) ? (X + (size_t)row * DM) : (row < TP ? p.in[0] + (size_t)row * DM : p.in[1] + (size_t)(row - TP) * DM);
; #pragma unroll
;                 for (int bj = 0; bj < 2; ++bj) {
;                     const int col = pn * 256 + bj * 128 + cw;
;                     const f32x4 s0 = *(const f32x4*)(src + col), s1 = *(const f32x4*)(src + col + 4);
;                     *(f32x4*)(X + (size_t)row * DM + col) = s0 + alpha * acc[ai][bj][m][0];
;                     *(f32x4*)(X + (size_t)row * DM + col + 4) = s1 + alpha * acc[ai][bj][m][1];
;                 }
;             }
.LBB0_326:
	s_andn2_b64 vcc, exec, s[6:7]
	s_cbranch_vccnz .LBB0_392
	s_cmp_lg_u32 s0, 2
	s_cbranch_scc1 .Lres_x
	v_mov_b32_e32 v134, s52
	v_mov_b32_e32 v135, s53
	s_branch .Lres_b
.Lres_x:
	v_readlane_b32 s38, v254, 42
	v_readlane_b32 s39, v254, 43
	v_readlane_b32 s50, v254, 44
	v_readlane_b32 s51, v254, 45
	s_nop 3
	s_sub_u32 s50, s50, 0x8000000
	s_subb_u32 s51, s51, 0
	v_mov_b32_e32 v134, s38
	v_mov_b32_e32 v135, s39
	v_mov_b32_e32 v136, s50
	v_mov_b32_e32 v137, s51
	v_cmp_gt_i32_e32 vcc, 0x4000, v154
	s_nop 1
	v_cndmask_b32_e32 v134, v136, v134, vcc
	v_cndmask_b32_e32 v135, v137, v135, vcc
.Lres_b:
	v_lshl_or_b32 v130, s26, 8, v146
	v_ashrrev_i32_e32 v131, 31, v130
	v_lshlrev_b64 v[130:131], 2, v[130:131]
	v_ashrrev_i32_e32 v155, 31, v154
	v_lshlrev_b64 v[136:137], 13, v[154:155]
	v_lshl_add_u64 v[136:137], v[136:137], 0, v[130:131]
	v_lshl_add_u64 v[130:131], v[134:135], 0, v[136:137]
	v_lshl_add_u64 v[132:133], s[52:53], 0, v[136:137]
	s_mov_b32 s6, 0x20000
	s_mov_b32 s7, 0
	s_mov_b32 s38, 0x80000
	s_mov_b32 s39, 0
	v_mov_b32_e32 v240, v132
	v_mov_b32_e32 v241, v133
	global_load_dwordx4 v[204:207], v[130:131], off
	global_load_dwordx4 v[208:211], v[130:131], off offset:16
	global_load_dwordx4 v[212:215], v[130:131], off offset:512
	global_load_dwordx4 v[216:219], v[130:131], off offset:528
	v_lshl_add_u64 v[130:131], v[130:131], 0, s[6:7]
	v_lshl_add_u64 v[132:133], v[132:133], 0, s[6:7]
	global_load_dwordx4 v[220:223], v[130:131], off
	global_load_dwordx4 v[224:227], v[130:131], off offset:16
	global_load_dwordx4 v[228:231], v[130:131], off offset:512
	global_load_dwordx4 v[232:235], v[130:131], off offset:528
	v_lshl_add_u64 v[130:131], v[130:131], 0, s[6:7]
	v_lshl_add_u64 v[132:133], v[132:133], 0, s[6:7]
	v_mov_b32_e32 v242, v132
	v_mov_b32_e32 v243, v133
	global_load_dwordx4 v[156:159], v[130:131], off
	global_load_dwordx4 v[160:163], v[130:131], off offset:16
	global_load_dwordx4 v[164:167], v[130:131], off offset:512
	global_load_dwordx4 v[172:175], v[130:131], off offset:528
	v_lshl_add_u64 v[130:131], v[130:131], 0, s[6:7]
	v_lshl_add_u64 v[132:133], v[132:133], 0, s[6:7]
	global_load_dwordx4 v[176:179], v[130:131], off
	global_load_dwordx4 v[180:183], v[130:131], off offset:16
	global_load_dwordx4 v[184:187], v[130:131], off offset:512
	global_load_dwordx4 v[236:239], v[130:131], off offset:528
	v_lshl_add_u64 v[130:131], v[130:131], 0, s[6:7]
	v_lshl_add_u64 v[132:133], v[132:133], 0, s[6:7]
	v_lshl_add_u64 v[130:131], v[130:131], 0, s[38:39]
	v_lshl_add_u64 v[132:133], v[132:133], 0, s[38:39]
	s_waitcnt vmcnt(8)
	v_pk_fma_f32 v[206:207], s[22:23], v[128:129], v[206:207]
	v_pk_fma_f32 v[204:205], s[8:9], v[126:127], v[204:205]
	v_pk_fma_f32 v[210:211], s[22:23], v[120:121], v[210:211]
	v_pk_fma_f32 v[208:209], s[8:9], v[118:119], v[208:209]
	v_pk_fma_f32 v[214:215], s[22:23], v[124:125], v[214:215]
	v_pk_fma_f32 v[212:213], s[8:9], v[122:123], v[212:213]
	v_pk_fma_f32 v[218:219], s[22:23], v[116:117], v[218:219]
	v_pk_fma_f32 v[216:217], s[8:9], v[114:115], v[216:217]
	v_pk_fma_f32 v[222:223], s[22:23], v[112:113], v[222:223]
	v_pk_fma_f32 v[220:221], s[8:9], v[110:111], v[220:221]
	v_pk_fma_f32 v[226:227], s[22:23], v[104:105], v[226:227]
	v_pk_fma_f32 v[224:225], s[8:9], v[102:103], v[224:225]
	v_pk_fma_f32 v[230:231], s[22:23], v[108:109], v[230:231]
	v_pk_fma_f32 v[228:229], s[8:9], v[106:107], v[228:229]
	v_pk_fma_f32 v[234:235], s[22:23], v[100:101], v[234:235]
	v_pk_fma_f32 v[232:233], s[8:9], v[98:99], v[232:233]
	global_store_dwordx4 v[240:241], v[204:207], off
	global_store_dwordx4 v[240:241], v[208:211], off offset:16
	global_store_dwordx4 v[240:241], v[212:215], off offset:512
	global_store_dwordx4 v[240:241], v[216:219], off offset:528
	v_lshl_add_u64 v[248:249], v[240:241], 0, s[6:7]
	global_store_dwordx4 v[248:249], v[220:223], off
	global_store_dwordx4 v[248:249], v[224:227], off offset:16
	global_store_dwordx4 v[248:249], v[228:231], off offset:512
	global_store_dwordx4 v[248:249], v[232:235], off offset:528
	v_mov_b32_e32 v244, v132
	v_mov_b32_e32 v245, v133
	global_load_dwordx4 v[204:207], v[130:131], off
	global_load_dwordx4 v[208:211], v[130:131], off offset:16
	global_load_dwordx4 v[212:215], v[130:131], off offset:512
	global_load_dwordx4 v[216:219], v[130:131], off offset:528
	v_lshl_add_u64 v[130:131], v[130:131], 0, s[6:7]
	v_lshl_add_u64 v[132:133], v[132:133], 0, s[6:7]
	global_load_dwordx4 v[220:223], v[130:131], off
	global_load_dwordx4 v[224:227], v[130:131], off offset:16
	global_load_dwordx4 v[228:231], v[130:131], off offset:512
	global_load_dwordx4 v[232:235], v[130:131], off offset:528
	v_lshl_add_u64 v[130:131], v[130:131], 0, s[6:7]
	v_lshl_add_u64 v[132:133], v[132:133], 0, s[6:7]
	s_waitcnt vmcnt(16)
; __device__ __forceinline__ void epilogue(const Params& p, int mode, int atomic, float alpha, const f32x4 (&acc)[2][2][4][2], int pm, int pn, int wr, int wc, int fr, int fq) {
;     ...
;     } else if (mode == EPI_RESX || mode == EPI_RESIN) {
;         float* X = p.out;
; #pragma unroll
;         for (int ai = 0; ai < 2; ++ai)
; #pragma unroll
;             for (int m = 0; m < 4; ++m) {
;                 const int row = row0 + ai * 128 + m * 16;
;                 const float* src = (mode == EPI_RESIN) ? (X + (size_t)row * DM) : (row < TP ? p.in[0] + (size_t)row * DM : p.in[1] + (size_t)(row - TP) * DM);
; #pragma unroll
;                 for (int bj = 0; bj < 2; ++bj) {
;                     const int col = pn * 256 + bj * 128 + cw;
;                     const f32x4 s0 = *(const f32x4*)(src + col), s1 = *(const f32x4*)(src + col + 4);
;                     *(f32x4*)(X + (size_t)row * DM + col) = s0 + alpha * acc[ai][bj][m][0];
;                     *(f32x4*)(X + (size_t)row * DM + col + 4) = s1 + alpha * acc[ai][bj][m][1];
;                 }
;             }
	v_pk_fma_f32 v[158:159], s[22:23], v[96:97], v[158:159]
	v_pk_fma_f32 v[156:157], s[8:9], v[94:95], v[156:157]
	v_pk_fma_f32 v[162:163], s[22:23], v[88:89], v[162:163]
	v_pk_fma_f32 v[160:161], s[8:9], v[86:87], v[160:161]
	v_pk_fma_f32 v[166:167], s[22:23], v[92:93], v[166:167]
	v_pk_fma_f32 v[164:165], s[8:9], v[90:91], v[164:165]
	v_pk_fma_f32 v[174:175], s[22:23], v[84:85], v[174:175]
	v_pk_fma_f32 v[172:173], s[8:9], v[82:83], v[172:173]
	v_pk_fma_f32 v[178:179], s[22:23], v[80:81], v[178:179]
	v_pk_fma_f32 v[176:177], s[8:9], v[78:79], v[176:177]
	v_pk_fma_f32 v[182:183], s[22:23], v[72:73], v[182:183]
	v_pk_fma_f32 v[180:181], s[8:9], v[70:71], v[180:181]
	v_pk_fma_f32 v[186:187], s[22:23], v[76:77], v[186:187]
	v_pk_fma_f32 v[184:185], s[8:9], v[74:75], v[184:185]
	v_pk_fma_f32 v[238:239], s[22:23], v[68:69], v[238:239]
	v_pk_fma_f32 v[236:237], s[8:9], v[66:67], v[236:237]
	global_store_dwordx4 v[242:243], v[156:159], off
	global_store_dwordx4 v[242:243], v[160:163], off offset:16
	global_store_dwordx4 v[242:243], v[164:167], off offset:512
	global_store_dwordx4 v[242:243], v[172:175], off offset:528
	v_lshl_add_u64 v[248:249], v[242:243], 0, s[6:7]
	global_store_dwordx4 v[248:249], v[176:179], off
	global_store_dwordx4 v[248:249], v[180:183], off offset:16
	global_store_dwordx4 v[248:249], v[184:187], off offset:512
	global_store_dwordx4 v[248:249], v[236:239], off offset:528
	v_mov_b32_e32 v246, v132
	v_mov_b32_e32 v247, v133
	global_load_dwordx4 v[156:159], v[130:131], off
	global_load_dwordx4 v[160:163], v[130:131], off offset:16
	global_load_dwordx4 v[164:167], v[130:131], off offset:512
	global_load_dwordx4 v[172:175], v[130:131], off offset:528
	v_lshl_add_u64 v[130:131], v[130:131], 0, s[6:7]
	v_lshl_add_u64 v[132:133], v[132:133], 0, s[6:7]
	global_load_dwordx4 v[176:179], v[130:131], off
	global_load_dwordx4 v[180:183], v[130:131], off offset:16
	global_load_dwordx4 v[184:187], v[130:131], off offset:512
	global_load_dwordx4 v[236:239], v[130:131], off offset:528
	v_lshl_add_u64 v[130:131], v[130:131], 0, s[6:7]
	v_lshl_add_u64 v[132:133], v[132:133], 0, s[6:7]
	s_waitcnt vmcnt(16)
	v_pk_fma_f32 v[206:207], s[22:23], v[64:65], v[206:207]
	v_pk_fma_f32 v[204:205], s[8:9], v[62:63], v[204:205]
	v_pk_fma_f32 v[210:211], s[22:23], v[56:57], v[210:211]
	v_pk_fma_f32 v[208:209], s[8:9], v[54:55], v[208:209]
	v_pk_fma_f32 v[214:215], s[22:23], v[60:61], v[214:215]
	v_pk_fma_f32 v[212:213], s[8:9], v[58:59], v[212:213]
	v_pk_fma_f32 v[218:219], s[22:23], v[52:53], v[218:219]
	v_pk_fma_f32 v[216:217], s[8:9], v[50:51], v[216:217]
	v_pk_fma_f32 v[222:223], s[22:23], v[48:49], v[222:223]
	v_pk_fma_f32 v[220:221], s[8:9], v[46:47], v[220:221]
	v_pk_fma_f32 v[226:227], s[22:23], v[40:41], v[226:227]
	v_pk_fma_f32 v[224:225], s[8:9], v[38:39], v[224:225]
	v_pk_fma_f32 v[230:231], s[22:23], v[44:45], v[230:231]
	v_pk_fma_f32 v[228:229], s[8:9], v[42:43], v[228:229]
	v_pk_fma_f32 v[234:235], s[22:23], v[36:37], v[234:235]
	v_pk_fma_f32 v[232:233], s[8:9], v[34:35], v[232:233]
	global_store_dwordx4 v[244:245], v[204:207], off
	global_store_dwordx4 v[244:245], v[208:211], off offset:16
	global_store_dwordx4 v[244:245], v[212:215], off offset:512
	global_store_dwordx4 v[244:245], v[216:219], off offset:528
	v_lshl_add_u64 v[248:249], v[244:245], 0, s[6:7]
	global_store_dwordx4 v[248:249], v[220:223], off
	global_store_dwordx4 v[248:249], v[224:227], off offset:16
	global_store_dwordx4 v[248:249], v[228:231], off offset:512
	global_store_dwordx4 v[248:249], v[232:235], off offset:528
	s_waitcnt vmcnt(8)
	v_pk_fma_f32 v[158:159], s[22:23], v[32:33], v[158:159]
	v_pk_fma_f32 v[156:157], s[8:9], v[30:31], v[156:157]
	v_pk_fma_f32 v[162:163], s[22:23], v[24:25], v[162:163]
	v_pk_fma_f32 v[160:161], s[8:9], v[22:23], v[160:161]
	v_pk_fma_f32 v[166:167], s[22:23], v[28:29], v[166:167]
	v_pk_fma_f32 v[164:165], s[8:9], v[26:27], v[164:165]
	v_pk_fma_f32 v[174:175], s[22:23], v[20:21], v[174:175]
	v_pk_fma_f32 v[172:173], s[8:9], v[18:19], v[172:173]
	v_pk_fma_f32 v[178:179], s[22:23], v[16:17], v[178:179]
	v_pk_fma_f32 v[176:177], s[8:9], v[14:15], v[176:177]
	v_pk_fma_f32 v[182:183], s[22:23], v[8:9], v[182:183]
	v_pk_fma_f32 v[180:181], s[8:9], v[6:7], v[180:181]
	v_pk_fma_f32 v[186:187], s[22:23], v[12:13], v[186:187]
	v_pk_fma_f32 v[184:185], s[8:9], v[10:11], v[184:185]
	v_pk_fma_f32 v[238:239], s[22:23], v[4:5], v[238:239]
	v_pk_fma_f32 v[236:237], s[8:9], v[2:3], v[236:237]
	global_store_dwordx4 v[246:247], v[156:159], off
	global_store_dwordx4 v[246:247], v[160:163], off offset:16
	global_store_dwordx4 v[246:247], v[164:167], off offset:512
	global_store_dwordx4 v[246:247], v[172:175], off offset:528
	v_lshl_add_u64 v[248:249], v[246:247], 0, s[6:7]
	global_store_dwordx4 v[248:249], v[176:179], off
	global_store_dwordx4 v[248:249], v[180:183], off offset:16
	global_store_dwordx4 v[248:249], v[184:187], off offset:512
	global_store_dwordx4 v[248:249], v[236:239], off offset:528

; __device__ __forceinline__ unsigned pk2(float lo, float hi) { unsigned r; asm("v_cvt_pk_bf16_f32 %0, %1, %2" : "=v"(r) : "v"(lo), "v"(hi)); return r; }
; __device__ __forceinline__ void load_row(const Params& p, int r, int mode, int lane, f32x4 (&v)[8]) {
;     float* X = p.out;
;     if (r < TP) {
; #pragma unroll
;         for (int j = 0; j < 8; ++j) v[j] = ((const f32x4*)(X + (size_t)r * DM))[j * 64 + lane];
;     } else {
;         const float* base = mode == 0 ? p.in[1] + (size_t)(r - TP) * DM : X + (size_t)r * DM;
;         const float alpha = mode == 1 ? 1.0f : 0.5f;
;         const float* P = (const float*)(p.ws + WS_PART) + (size_t)(r - TP) * DM;
; #pragma unroll
;         for (int j = 0; j < 8; ++j) {
;             f32x4 a = (f32x4){0.f, 0.f, 0.f, 0.f};
; #pragma unroll
;             for (int q = 0; q < 8; ++q) a += ((const f32x4*)(P + (size_t)q * 512 * DM))[j * 64 + lane];
;             v[j] = ((const f32x4*)base)[j * 64 + lane] + alpha * a;
;             if (mode < 2) ((f32x4*)(X + (size_t)r * DM))[j * 64 + lane] = v[j];
;         }
;     }
; }
; __device__ __forceinline__ void phase_norm(const Params& p, unsigned char* sm, int mode, const int TIDX, const int BIDX) {
;     const int tid = TIDX, wid = tid >> 6, lane = tid & 63, wgid = BIDX * 8 + wid, nw = gridDim.x * 8;
;     float* X = p.out;
;     const float* g = mode == 0 ? p.in[12] : (mode == 1 ? p.in[26] : p.in[29]);
;     for (int r = wgid; r < TT; r += nw) {
;         f32x4 v[8]; float s = 0.f;
;         load_row(p, r, mode, lane, v);
; #pragma unroll
;         for (int j = 0; j < 8; ++j) s += v[j][0] * v[j][0] + v[j][1] * v[j][1] + v[j][2] * v[j][2] + v[j][3] * v[j][3];
;         s = wave_sum(s); const float rs = rsqrtf(s * (1.0f / DM) + EPS);
;         if (mode < 2) {
;             bf16_t* o = (bf16_t*)(p.ws + WS_ABUF) + (size_t)r * DM;
; #pragma unroll
;             for (int j = 0; j < 8; ++j) { const f32x4 gg = ((const f32x4*)g)[j * 64 + lane]; u32x2 w; w.x = pk2(v[j][0] * rs * gg[0], v[j][1] * rs * gg[1]); w.y = pk2(v[j][2] * rs * gg[2], v[j][3] * rs * gg[3]); ((u32x2*)o)[j * 64 + lane] = w; }
.LBB0_524:
	s_and_b64 vcc, exec, s[6:7]
	s_mov_b32 s24, 0x44000
	s_mov_b32 s25, 0x48000
	s_mov_b32 s40, 0x4c000
	s_mov_b32 s41, 0x54000
	s_cbranch_vccz .LBB0_532
	s_waitcnt lgkmcnt(0)
	v_readlane_b32 s0, v254, 41
	v_ashrrev_i32_e32 v2, 6, v199
	s_lshl_b32 s12, s0, 3
	v_add_u32_e32 v0, s12, v2
	s_movk_i32 s0, 0x4200
	v_cmp_gt_i32_e32 vcc, s0, v0
	s_and_saveexec_b64 s[6:7], vcc
	s_cbranch_execz .LBB0_533
	v_cmp_lt_i32_e32 vcc, v189, v188
	v_and_b32_e32 v4, 63, v199
	v_or_b32_e32 v6, 0x100, v4
	v_cndmask_b32_e32 v0, v169, v189, vcc
	v_cmp_lt_i32_e32 vcc, v190, v188
	v_lshlrev_b32_e32 v66, 2, v0
	v_readlane_b32 s48, v254, 58
	v_cndmask_b32_e32 v0, v169, v190, vcc
	v_cmp_lt_i32_e32 vcc, v191, v188
	v_lshlrev_b32_e32 v67, 2, v0
	v_readlane_b32 s8, v254, 4
	v_cndmask_b32_e32 v0, v169, v191, vcc
	v_cmp_lt_i32_e32 vcc, v192, v188
	v_or_b32_e32 v8, 0x140, v4
	s_waitcnt vmcnt(0)
	v_lshlrev_b32_e32 v68, 2, v0
	v_cndmask_b32_e32 v0, v169, v192, vcc
	v_cmp_lt_i32_e32 vcc, v193, v188
	v_readlane_b32 s56, v255, 2
	v_readlane_b32 s57, v255, 3
	v_lshlrev_b32_e32 v14, 4, v6
	v_mov_b32_e32 v15, v1
	v_readlane_b32 s9, v254, 5
	v_or_b32_e32 v10, 0x180, v4
	v_lshlrev_b32_e32 v69, 2, v0
	v_cndmask_b32_e32 v0, v169, v193, vcc
	v_cmp_lt_i32_e32 vcc, v194, v188
	v_lshl_add_u64 v[36:37], s[56:57], 0, v[14:15]
	v_lshlrev_b32_e32 v14, 4, v8
	s_load_dword s0, s[8:9], 0x0
	v_or_b32_e32 v12, 0x1c0, v4
	v_lshlrev_b32_e32 v70, 2, v0
	v_cndmask_b32_e32 v0, v169, v194, vcc
	v_lshl_add_u64 v[38:39], s[56:57], 0, v[14:15]
	v_lshlrev_b32_e32 v14, 4, v10
	v_lshlrev_b32_e32 v71, 2, v0
	v_lshlrev_b32_e32 v0, 4, v4
	v_readlane_b32 s49, v254, 59
	v_readlane_b32 s50, v254, 60
	v_readlane_b32 s51, v254, 61
	v_readlane_b32 s52, v254, 62
	v_readlane_b32 s53, v254, 63
	v_readlane_b32 s54, v255, 0
	v_readlane_b32 s55, v255, 1
	v_readlane_b32 s58, v255, 4
	v_readlane_b32 s59, v255, 5
	v_readlane_b32 s60, v255, 6
	v_readlane_b32 s61, v255, 7
	v_readlane_b32 s62, v255, 8
	v_readlane_b32 s63, v255, 9
	v_lshl_add_u64 v[40:41], s[56:57], 0, v[14:15]
	v_lshlrev_b32_e32 v14, 4, v12
	v_lshl_add_u64 v[34:35], s[56:57], 0, v[0:1]
	v_lshl_add_u64 v[42:43], s[56:57], 0, v[14:15]
	v_readlane_b32 s48, v255, 20
	v_readlane_b32 s60, v255, 32
	v_readlane_b32 s61, v255, 33
	v_readlane_b32 s62, v255, 34
	v_readlane_b32 s63, v255, 35
	s_mov_b64 s[20:21], s[60:61]
	s_waitcnt lgkmcnt(0)
	s_lshl_b32 s8, s0, 3
	s_mov_b64 s[22:23], s[62:63]
	s_add_u32 s10, s22, 0x1afe4000
	s_addc_u32 s11, s23, 0
	v_ashrrev_i32_e32 v3, 31, v2
	s_ashr_i32 s13, s12, 31
	v_lshl_add_u64 v[46:47], v[2:3], 0, s[12:13]
	v_lshlrev_b64 v[2:3], 13, v[46:47]
	v_lshlrev_b32_e32 v14, 3, v4
	v_or_b32_e32 v2, v2, v0
	v_lshl_add_u64 v[14:15], s[22:23], 0, v[14:15]
	s_mov_b64 s[14:15], 0x6284000
	s_ashr_i32 s9, s8, 31
	v_lshl_add_u64 v[2:3], s[20:21], 0, v[2:3]
	s_mov_b64 s[12:13], 0x1000
	v_lshl_add_u64 v[44:45], v[14:15], 0, s[14:15]
	v_lshl_add_u64 v[48:49], v[2:3], 0, s[12:13]
	s_lshl_b64 s[12:13], s[8:9], 13
	s_mov_b64 s[14:15], 0
	v_lshlrev_b32_e32 v50, 4, v4
	v_lshlrev_b32_e32 v52, 4, v6
	v_lshlrev_b32_e32 v54, 4, v8
	v_lshlrev_b32_e32 v56, 4, v10
	v_lshlrev_b32_e32 v58, 4, v12
	v_readlane_b32 s49, v255, 21
	v_readlane_b32 s50, v255, 22
	v_readlane_b32 s51, v255, 23
	v_readlane_b32 s52, v255, 24
	v_readlane_b32 s53, v255, 25
	v_readlane_b32 s54, v255, 26
	v_readlane_b32 s55, v255, 27
	v_readlane_b32 s56, v255, 28
	v_readlane_b32 s57, v255, 29
	v_readlane_b32 s58, v255, 30
	v_readlane_b32 s59, v255, 31
	global_load_dwordx4 v[204:207], v[34:35], off
	global_load_dwordx4 v[208:211], v[34:35], off offset:1024
	global_load_dwordx4 v[212:215], v[34:35], off offset:2048
	global_load_dwordx4 v[216:219], v[34:35], off offset:3072
	global_load_dwordx4 v[220:223], v[36:37], off
	global_load_dwordx4 v[224:227], v[38:39], off
	global_load_dwordx4 v[228:231], v[40:41], off
	global_load_dwordx4 v[232:235], v[42:43], off
	s_waitcnt vmcnt(0)
	s_branch .LBB0_528
.LBB0_527:
	s_or_b64 exec, exec, s[16:17]
	s_waitcnt vmcnt(7)
	v_mul_f32_e32 v0, v7, v7
	s_waitcnt vmcnt(6)
	v_mul_f32_e32 v51, v3, v3
	v_fmac_f32_e32 v0, v6, v6
	v_fmac_f32_e32 v51, v2, v2
	v_fmac_f32_e32 v0, v8, v8
	v_fmac_f32_e32 v51, v4, v4
	v_fmac_f32_e32 v0, v9, v9
	v_fmac_f32_e32 v51, v5, v5
	v_add_f32_e32 v0, v0, v51
	s_waitcnt vmcnt(5)
	v_mul_f32_e32 v51, v11, v11
	v_fmac_f32_e32 v51, v10, v10
	v_fmac_f32_e32 v51, v12, v12
	v_fmac_f32_e32 v51, v13, v13
	v_add_f32_e32 v0, v51, v0
	s_waitcnt vmcnt(4)
	v_mul_f32_e32 v51, v15, v15
	s_waitcnt vmcnt(2)
	v_pk_mul_f32 v[80:81], v[22:23], v[22:23]
	v_pk_mul_f32 v[82:83], v[18:19], v[18:19]
	v_fmac_f32_e32 v51, v14, v14
	v_pk_mul_f32 v[76:77], v[24:25], v[24:25]
	v_pk_mul_f32 v[78:79], v[20:21], v[20:21]
	v_mov_b32_e32 v84, v80
	v_mov_b32_e32 v85, v82
	v_mov_b32_e32 v82, v81
	v_fmac_f32_e32 v51, v16, v16
	v_pk_add_f32 v[80:81], v[84:85], v[82:83]
	v_mov_b32_e32 v82, v76
	v_mov_b32_e32 v83, v78
	v_fmac_f32_e32 v51, v17, v17
	v_pk_add_f32 v[80:81], v[82:83], v[80:81]
	v_mov_b32_e32 v78, v77
	v_add_f32_e32 v0, v51, v0
	v_pk_add_f32 v[76:77], v[78:79], v[80:81]
	s_waitcnt vmcnt(0)
	v_pk_mul_f32 v[72:73], v[30:31], v[30:31]
	v_pk_mul_f32 v[74:75], v[26:27], v[26:27]
	v_add_f32_e32 v0, v77, v0
	v_pk_mul_f32 v[62:63], v[32:33], v[32:33]
	v_pk_mul_f32 v[64:65], v[28:29], v[28:29]
	v_add_f32_e32 v0, v76, v0
	v_mov_b32_e32 v76, v72
	v_mov_b32_e32 v77, v74
	v_mov_b32_e32 v74, v73
	v_pk_add_f32 v[72:73], v[76:77], v[74:75]
	v_mov_b32_e32 v74, v62
	v_mov_b32_e32 v75, v64
	v_pk_add_f32 v[72:73], v[74:75], v[72:73]
	v_mov_b32_e32 v64, v63
	v_pk_add_f32 v[62:63], v[64:65], v[72:73]
	v_lshlrev_b64 v[60:61], 12, v[60:61]
	v_add_f32_e32 v0, v63, v0
	v_add_f32_e32 v0, v62, v0
	v_mov_b64_e32 v[62:63], v[204:205]
	v_mov_b64_e32 v[64:65], v[206:207]
	ds_bpermute_b32 v51, v66, v0
	v_lshl_add_u64 v[46:47], v[46:47], 0, s[8:9]
	s_movk_i32 s0, 0x41ff
	v_lshl_add_u64 v[48:49], v[48:49], 0, s[12:13]
	s_waitcnt lgkmcnt(0)
; __device__ __forceinline__ unsigned pk2(float lo, float hi) { unsigned r; asm("v_cvt_pk_bf16_f32 %0, %1, %2" : "=v"(r) : "v"(lo), "v"(hi)); return r; }
; __device__ __forceinline__ void load_row(const Params& p, int r, int mode, int lane, f32x4 (&v)[8]) {
;     float* X = p.out;
;     if (r < TP) {
; #pragma unroll
;         for (int j = 0; j < 8; ++j) v[j] = ((const f32x4*)(X + (size_t)r * DM))[j * 64 + lane];
;     } else {
;         const float* base = mode == 0 ? p.in[1] + (size_t)(r - TP) * DM : X + (size_t)r * DM;
;         const float alpha = mode == 1 ? 1.0f : 0.5f;
;         const float* P = (const float*)(p.ws + WS_PART) + (size_t)(r - TP) * DM;
; #pragma unroll
;         for (int j = 0; j < 8; ++j) {
;             f32x4 a = (f32x4){0.f, 0.f, 0.f, 0.f};
; #pragma unroll
;             for (int q = 0; q < 8; ++q) a += ((const f32x4*)(P + (size_t)q * 512 * DM))[j * 64 + lane];
;             v[j] = ((const f32x4*)base)[j * 64 + lane] + alpha * a;
;             if (mode < 2) ((f32x4*)(X + (size_t)r * DM))[j * 64 + lane] = v[j];
;         }
;     }
; }
; __device__ __forceinline__ void phase_norm(const Params& p, unsigned char* sm, int mode, const int TIDX, const int BIDX) {
;     const int tid = TIDX, wid = tid >> 6, lane = tid & 63, wgid = BIDX * 8 + wid, nw = gridDim.x * 8;
;     float* X = p.out;
;     const float* g = mode == 0 ? p.in[12] : (mode == 1 ? p.in[26] : p.in[29]);
;     for (int r = wgid; r < TT; r += nw) {
;         f32x4 v[8]; float s = 0.f;
;         load_row(p, r, mode, lane, v);
; #pragma unroll
;         for (int j = 0; j < 8; ++j) s += v[j][0] * v[j][0] + v[j][1] * v[j][1] + v[j][2] * v[j][2] + v[j][3] * v[j][3];
;         s = wave_sum(s); const float rs = rsqrtf(s * (1.0f / DM) + EPS);
;         if (mode < 2) {
;             bf16_t* o = (bf16_t*)(p.ws + WS_ABUF) + (size_t)r * DM;
; #pragma unroll
;             for (int j = 0; j < 8; ++j) { const f32x4 gg = ((const f32x4*)g)[j * 64 + lane]; u32x2 w; w.x = pk2(v[j][0] * rs * gg[0], v[j][1] * rs * gg[1]); w.y = pk2(v[j][2] * rs * gg[2], v[j][3] * rs * gg[3]); ((u32x2*)o)[j * 64 + lane] = w; }
	v_add_f32_e32 v0, v0, v51
	ds_bpermute_b32 v51, v67, v0
	s_waitcnt lgkmcnt(0)
	v_add_f32_e32 v0, v0, v51
	ds_bpermute_b32 v51, v68, v0
	s_waitcnt lgkmcnt(0)
	v_add_f32_e32 v0, v0, v51
	ds_bpermute_b32 v51, v69, v0
	s_waitcnt lgkmcnt(0)
	v_add_f32_e32 v0, v0, v51
	ds_bpermute_b32 v51, v70, v0
	s_waitcnt lgkmcnt(0)
	v_add_f32_e32 v0, v0, v51
	ds_bpermute_b32 v51, v71, v0
	s_waitcnt lgkmcnt(0)
	v_add_f32_e32 v0, v0, v51
	v_fmamk_f32 v0, v0, 0x3a000000, v168
	v_cmp_gt_f32_e32 vcc, s97, v0
	v_mul_f32_e32 v51, 0x4b800000, v0
	s_nop 0
	v_cndmask_b32_e32 v0, v0, v51, vcc
	v_rsq_f32_e32 v0, v0
	s_nop 0
	v_mul_f32_e32 v51, 0x45800000, v0
	v_cndmask_b32_e32 v0, v0, v51, vcc
	v_mul_f32_e32 v6, v6, v0
	v_mul_f32_e32 v7, v7, v0
	v_mul_f32_e32 v2, v2, v0
	v_mul_f32_e32 v3, v3, v0
	v_cmp_lt_i32_e32 vcc, s0, v46
	s_or_b64 s[14:15], vcc, s[14:15]
	v_mul_f32_e32 v6, v62, v6
	v_mul_f32_e32 v7, v63, v7
	v_cvt_pk_bf16_f32 v62, v6, v7
	v_mul_f32_e32 v6, v8, v0
	v_mul_f32_e32 v7, v9, v0
	v_mul_f32_e32 v6, v64, v6
	v_mul_f32_e32 v7, v65, v7
	v_cvt_pk_bf16_f32 v63, v6, v7
	v_lshl_add_u64 v[6:7], v[44:45], 0, v[60:61]
	global_store_dwordx2 v[6:7], v[62:63], off
	v_mov_b64_e32 v[60:61], v[208:209]
	v_mov_b64_e32 v[62:63], v[210:211]
	v_mul_f32_e32 v8, v10, v0
	v_mul_f32_e32 v2, v60, v2
	v_mul_f32_e32 v3, v61, v3
	v_cvt_pk_bf16_f32 v2, v2, v3
	v_mul_f32_e32 v3, v4, v0
	v_mul_f32_e32 v3, v62, v3
	v_mul_f32_e32 v4, v5, v0
	v_mul_f32_e32 v4, v63, v4
	v_cvt_pk_bf16_f32 v3, v3, v4
	global_store_dwordx2 v[6:7], v[2:3], off offset:512
	v_mov_b64_e32 v[2:3], v[212:213]
	v_mov_b64_e32 v[4:5], v[214:215]
	v_mul_f32_e32 v2, v2, v8
	v_mul_f32_e32 v8, v11, v0
	v_mul_f32_e32 v3, v3, v8
	v_cvt_pk_bf16_f32 v2, v2, v3
	v_mul_f32_e32 v3, v12, v0
	v_mul_f32_e32 v3, v4, v3
	v_mul_f32_e32 v4, v13, v0
	v_mul_f32_e32 v4, v5, v4
	v_cvt_pk_bf16_f32 v3, v3, v4
	global_store_dwordx2 v[6:7], v[2:3], off offset:1024
	v_mov_b64_e32 v[2:3], v[216:217]
	v_mov_b64_e32 v[4:5], v[218:219]
	v_mul_f32_e32 v8, v14, v0
	v_mul_f32_e32 v2, v2, v8
	v_mul_f32_e32 v8, v15, v0
	v_mul_f32_e32 v3, v3, v8
	v_cvt_pk_bf16_f32 v2, v2, v3
	v_mul_f32_e32 v3, v16, v0
	v_mul_f32_e32 v3, v4, v3
	v_mul_f32_e32 v4, v17, v0
	v_mul_f32_e32 v4, v5, v4
	v_cvt_pk_bf16_f32 v3, v3, v4
	global_store_dwordx2 v[6:7], v[2:3], off offset:1536
	v_mov_b64_e32 v[2:3], v[220:221]
	v_mov_b64_e32 v[4:5], v[222:223]
	v_mul_f32_e32 v8, v18, v0
	v_mul_f32_e32 v2, v2, v8
	v_mul_f32_e32 v8, v19, v0
	v_mul_f32_e32 v3, v3, v8
	v_cvt_pk_bf16_f32 v2, v2, v3
	v_mul_f32_e32 v3, v20, v0
	v_mul_f32_e32 v3, v4, v3
	v_mul_f32_e32 v4, v21, v0
	v_mul_f32_e32 v4, v5, v4
	v_cvt_pk_bf16_f32 v3, v3, v4
	global_store_dwordx2 v[6:7], v[2:3], off offset:2048
	v_mov_b64_e32 v[2:3], v[224:225]
	v_mov_b64_e32 v[4:5], v[226:227]
	v_mul_f32_e32 v8, v22, v0
	v_mul_f32_e32 v2, v8, v2
	v_mul_f32_e32 v8, v23, v0
	v_mul_f32_e32 v3, v8, v3
	v_cvt_pk_bf16_f32 v2, v2, v3
	v_mul_f32_e32 v3, v24, v0
	v_mul_f32_e32 v3, v3, v4
	v_mul_f32_e32 v4, v25, v0
	v_mul_f32_e32 v4, v4, v5
	v_cvt_pk_bf16_f32 v3, v3, v4
	global_store_dwordx2 v[6:7], v[2:3], off offset:2560
	v_mov_b64_e32 v[2:3], v[228:229]
	v_mov_b64_e32 v[4:5], v[230:231]
	v_mul_f32_e32 v8, v26, v0
	v_mul_f32_e32 v2, v8, v2
	v_mul_f32_e32 v8, v27, v0
	v_mul_f32_e32 v3, v8, v3
	v_cvt_pk_bf16_f32 v2, v2, v3
	v_mul_f32_e32 v3, v28, v0
	v_mul_f32_e32 v3, v3, v4
	v_mul_f32_e32 v4, v29, v0
	v_mul_f32_e32 v4, v4, v5
	v_cvt_pk_bf16_f32 v3, v3, v4
	global_store_dwordx2 v[6:7], v[2:3], off offset:3072
	v_mov_b64_e32 v[2:3], v[232:233]
	v_mov_b64_e32 v[4:5], v[234:235]
	v_mul_f32_e32 v8, v30, v0
	v_mul_f32_e32 v2, v8, v2
	v_mul_f32_e32 v8, v31, v0
	v_mul_f32_e32 v3, v8, v3
	v_cvt_pk_bf16_f32 v2, v2, v3
	v_mul_f32_e32 v3, v32, v0
	v_mul_f32_e32 v3, v3, v4
	v_mul_f32_e32 v0, v33, v0
	v_mul_f32_e32 v0, v0, v5
	v_cvt_pk_bf16_f32 v3, v3, v0
	global_store_dwordx2 v[6:7], v[2:3], off offset:3584
	s_andn2_b64 exec, exec, s[14:15]
	s_cbranch_execz .LBB0_533
.LBB0_528:
	v_cmp_lt_i32_e32 vcc, s81, v46
	s_and_saveexec_b64 s[16:17], vcc
	s_xor_b64 s[16:17], exec, s[16:17]
	s_cbranch_execz .LBB0_530
	v_readlane_b32 s22, v254, 44
	v_readlane_b32 s23, v254, 45
	v_readlane_b32 s24, v255, 32
	v_readlane_b32 s25, v255, 33
	v_mov_b32_e32 v51, v1
	v_add_u32_e32 v2, 0xffffc000, v46
	v_mov_b32_e32 v3, v1
	v_lshlrev_b64 v[2:3], 13, v[2:3]
	s_waitcnt vmcnt(0)
	v_lshl_add_u64 v[152:153], s[10:11], 0, v[2:3]
	v_lshl_add_u64 v[152:153], v[152:153], 0, v[50:51]
	v_lshl_add_u64 v[150:151], s[22:23], 0, v[2:3]
	v_lshl_add_u64 v[150:151], v[150:151], 0, v[50:51]
	v_mov_b32_e32 v0, v46
	v_lshlrev_b64 v[2:3], 13, v[0:1]
	v_lshl_add_u64 v[156:157], s[24:25], 0, v[2:3]
	v_lshl_add_u64 v[156:157], v[156:157], 0, v[50:51]
	s_mov_b32 s18, 0x400000
	s_mov_b32 s19, 0
	s_mov_b32 s20, 0x1000
	s_mov_b32 s21, 0
	v_mov_b64_e32 v[148:149], v[152:153]
	v_mov_b64_e32 v[154:155], v[150:151]
	v_mov_b64_e32 v[158:159], v[156:157]
	global_load_dwordx4 v[76:79], v[148:149], off
	global_load_dwordx4 v[80:83], v[148:149], off offset:1024
	v_lshl_add_u64 v[148:149], v[148:149], 0, s[18:19]
	global_load_dwordx4 v[84:87], v[148:149], off
	global_load_dwordx4 v[88:91], v[148:149], off offset:1024
	v_lshl_add_u64 v[148:149], v[148:149], 0, s[18:19]
	global_load_dwordx4 v[92:95], v[148:149], off
	global_load_dwordx4 v[96:99], v[148:149], off offset:1024
	v_lshl_add_u64 v[148:149], v[148:149], 0, s[18:19]
	global_load_dwordx4 v[100:103], v[148:149], off
	global_load_dwordx4 v[104:107], v[148:149], off offset:1024
	v_lshl_add_u64 v[148:149], v[148:149], 0, s[18:19]
	global_load_dwordx4 v[108:111], v[148:149], off
	global_load_dwordx4 v[112:115], v[148:149], off offset:1024
	v_lshl_add_u64 v[148:149], v[148:149], 0, s[18:19]
	global_load_dwordx4 v[116:119], v[148:149], off
	global_load_dwordx4 v[120:123], v[148:149], off offset:1024
	v_lshl_add_u64 v[148:149], v[148:149], 0, s[18:19]
	global_load_dwordx4 v[124:127], v[148:149], off
	global_load_dwordx4 v[128:131], v[148:149], off offset:1024
	v_lshl_add_u64 v[148:149], v[148:149], 0, s[18:19]
	global_load_dwordx4 v[132:135], v[148:149], off
	global_load_dwordx4 v[136:139], v[148:149], off offset:1024
	global_load_dwordx4 v[140:143], v[154:155], off
	global_load_dwordx4 v[144:147], v[154:155], off offset:1024
	s_waitcnt vmcnt(0)
; __device__ __forceinline__ void load_row(const Params& p, int r, int mode, int lane, f32x4 (&v)[8]) {
;     ...
;         const float* P = (const float*)(p.ws + WS_PART) + (size_t)(r - TP) * DM;
; #pragma unroll
;         for (int j = 0; j < 8; ++j) {
;             f32x4 a = (f32x4){0.f, 0.f, 0.f, 0.f};
; #pragma unroll
;             for (int q = 0; q < 8; ++q) a += ((const f32x4*)(P + (size_t)q * 512 * DM))[j * 64 + lane];
;             v[j] = ((const f32x4*)base)[j * 64 + lane] + alpha * a;
;             if (mode < 2) ((f32x4*)(X + (size_t)r * DM))[j * 64 + lane] = v[j];
;         }
	v_pk_add_f32 v[78:79], v[78:79], 0 op_sel_hi:[1,0]
	v_pk_add_f32 v[76:77], v[76:77], 0 op_sel_hi:[1,0]
	v_pk_add_f32 v[78:79], v[78:79], v[86:87]
	v_pk_add_f32 v[76:77], v[76:77], v[84:85]
	v_pk_add_f32 v[78:79], v[78:79], v[94:95]
	v_pk_add_f32 v[76:77], v[76:77], v[92:93]
	v_pk_add_f32 v[78:79], v[78:79], v[102:103]
	v_pk_add_f32 v[76:77], v[76:77], v[100:101]
	v_pk_add_f32 v[78:79], v[78:79], v[110:111]
	v_pk_add_f32 v[76:77], v[76:77], v[108:109]
	v_pk_add_f32 v[78:79], v[78:79], v[118:119]
	v_pk_add_f32 v[76:77], v[76:77], v[116:117]
	v_pk_add_f32 v[78:79], v[78:79], v[126:127]
	v_pk_add_f32 v[76:77], v[76:77], v[124:125]
	v_pk_add_f32 v[78:79], v[78:79], v[134:135]
	v_pk_add_f32 v[76:77], v[76:77], v[132:133]
	v_pk_fma_f32 v[8:9], v[78:79], 0.5, v[142:143] op_sel_hi:[1,0,1]
	v_pk_fma_f32 v[6:7], v[76:77], 0.5, v[140:141] op_sel_hi:[1,0,1]
	global_store_dwordx4 v[158:159], v[6:9], off
	v_pk_add_f32 v[82:83], v[82:83], 0 op_sel_hi:[1,0]
	v_pk_add_f32 v[80:81], v[80:81], 0 op_sel_hi:[1,0]
	v_pk_add_f32 v[82:83], v[82:83], v[90:91]
	v_pk_add_f32 v[80:81], v[80:81], v[88:89]
	v_pk_add_f32 v[82:83], v[82:83], v[98:99]
	v_pk_add_f32 v[80:81], v[80:81], v[96:97]
	v_pk_add_f32 v[82:83], v[82:83], v[106:107]
	v_pk_add_f32 v[80:81], v[80:81], v[104:105]
	v_pk_add_f32 v[82:83], v[82:83], v[114:115]
	v_pk_add_f32 v[80:81], v[80:81], v[112:113]
	v_pk_add_f32 v[82:83], v[82:83], v[122:123]
	v_pk_add_f32 v[80:81], v[80:81], v[120:121]
	v_pk_add_f32 v[82:83], v[82:83], v[130:131]
	v_pk_add_f32 v[80:81], v[80:81], v[128:129]
	v_pk_add_f32 v[82:83], v[82:83], v[138:139]
	v_pk_add_f32 v[80:81], v[80:81], v[136:137]
	v_pk_fma_f32 v[4:5], v[82:83], 0.5, v[146:147] op_sel_hi:[1,0,1]
	v_pk_fma_f32 v[2:3], v[80:81], 0.5, v[144:145] op_sel_hi:[1,0,1]
	global_store_dwordx4 v[158:159], v[2:5], off offset:1024
	v_mov_b64_e32 v[148:149], v[152:153]
	v_mov_b64_e32 v[154:155], v[150:151]
	v_mov_b64_e32 v[158:159], v[156:157]
	global_load_dwordx4 v[76:79], v[148:149], off offset:2048
	global_load_dwordx4 v[80:83], v[148:149], off offset:3072
	v_lshl_add_u64 v[148:149], v[148:149], 0, s[18:19]
	global_load_dwordx4 v[84:87], v[148:149], off offset:2048
	global_load_dwordx4 v[88:91], v[148:149], off offset:3072
	v_lshl_add_u64 v[148:149], v[148:149], 0, s[18:19]
	global_load_dwordx4 v[92:95], v[148:149], off offset:2048
	global_load_dwordx4 v[96:99], v[148:149], off offset:3072
	v_lshl_add_u64 v[148:149], v[148:149], 0, s[18:19]
	global_load_dwordx4 v[100:103], v[148:149], off offset:2048
	global_load_dwordx4 v[104:107], v[148:149], off offset:3072
	v_lshl_add_u64 v[148:149], v[148:149], 0, s[18:19]
	global_load_dwordx4 v[108:111], v[148:149], off offset:2048
	global_load_dwordx4 v[112:115], v[148:149], off offset:3072
	v_lshl_add_u64 v[148:149], v[148:149], 0, s[18:19]
	global_load_dwordx4 v[116:119], v[148:149], off offset:2048
	global_load_dwordx4 v[120:123], v[148:149], off offset:3072
	v_lshl_add_u64 v[148:149], v[148:149], 0, s[18:19]
	global_load_dwordx4 v[124:127], v[148:149], off offset:2048
	global_load_dwordx4 v[128:131], v[148:149], off offset:3072
	v_lshl_add_u64 v[148:149], v[148:149], 0, s[18:19]
	global_load_dwordx4 v[132:135], v[148:149], off offset:2048
	global_load_dwordx4 v[136:139], v[148:149], off offset:3072
	global_load_dwordx4 v[140:143], v[154:155], off offset:2048
	global_load_dwordx4 v[144:147], v[154:155], off offset:3072
	s_waitcnt vmcnt(0)
	v_pk_add_f32 v[78:79], v[78:79], 0 op_sel_hi:[1,0]
	v_pk_add_f32 v[76:77], v[76:77], 0 op_sel_hi:[1,0]
	v_pk_add_f32 v[78:79], v[78:79], v[86:87]
	v_pk_add_f32 v[76:77], v[76:77], v[84:85]
	v_pk_add_f32 v[78:79], v[78:79], v[94:95]
	v_pk_add_f32 v[76:77], v[76:77], v[92:93]
	v_pk_add_f32 v[78:79], v[78:79], v[102:103]
	v_pk_add_f32 v[76:77], v[76:77], v[100:101]
	v_pk_add_f32 v[78:79], v[78:79], v[110:111]
	v_pk_add_f32 v[76:77], v[76:77], v[108:109]
	v_pk_add_f32 v[78:79], v[78:79], v[118:119]
	v_pk_add_f32 v[76:77], v[76:77], v[116:117]
	v_pk_add_f32 v[78:79], v[78:79], v[126:127]
	v_pk_add_f32 v[76:77], v[76:77], v[124:125]
	v_pk_add_f32 v[78:79], v[78:79], v[134:135]
	v_pk_add_f32 v[76:77], v[76:77], v[132:133]
	v_pk_fma_f32 v[12:13], v[78:79], 0.5, v[142:143] op_sel_hi:[1,0,1]
	v_pk_fma_f32 v[10:11], v[76:77], 0.5, v[140:141] op_sel_hi:[1,0,1]
	global_store_dwordx4 v[158:159], v[10:13], off offset:2048
	v_pk_add_f32 v[82:83], v[82:83], 0 op_sel_hi:[1,0]
	v_pk_add_f32 v[80:81], v[80:81], 0 op_sel_hi:[1,0]
	v_pk_add_f32 v[82:83], v[82:83], v[90:91]
	v_pk_add_f32 v[80:81], v[80:81], v[88:89]
	v_pk_add_f32 v[82:83], v[82:83], v[98:99]
	v_pk_add_f32 v[80:81], v[80:81], v[96:97]
	v_pk_add_f32 v[82:83], v[82:83], v[106:107]
	v_pk_add_f32 v[80:81], v[80:81], v[104:105]
	v_pk_add_f32 v[82:83], v[82:83], v[114:115]
	v_pk_add_f32 v[80:81], v[80:81], v[112:113]
	v_pk_add_f32 v[82:83], v[82:83], v[122:123]
	v_pk_add_f32 v[80:81], v[80:81], v[120:121]
	v_pk_add_f32 v[82:83], v[82:83], v[130:131]
	v_pk_add_f32 v[80:81], v[80:81], v[128:129]
	v_pk_add_f32 v[82:83], v[82:83], v[138:139]
	v_pk_add_f32 v[80:81], v[80:81], v[136:137]
	v_pk_fma_f32 v[16:17], v[82:83], 0.5, v[146:147] op_sel_hi:[1,0,1]
	v_pk_fma_f32 v[14:15], v[80:81], 0.5, v[144:145] op_sel_hi:[1,0,1]
	global_store_dwordx4 v[158:159], v[14:17], off offset:3072
	v_lshl_add_u64 v[148:149], v[152:153], 0, s[20:21]
	v_lshl_add_u64 v[154:155], v[150:151], 0, s[20:21]
	v_lshl_add_u64 v[158:159], v[156:157], 0, s[20:21]
	global_load_dwordx4 v[76:79], v[148:149], off
	global_load_dwordx4 v[80:83], v[148:149], off offset:1024
	v_lshl_add_u64 v[148:149], v[148:149], 0, s[18:19]
	global_load_dwordx4 v[84:87], v[148:149], off
	global_load_dwordx4 v[88:91], v[148:149], off offset:1024
	v_lshl_add_u64 v[148:149], v[148:149], 0, s[18:19]
	global_load_dwordx4 v[92:95], v[148:149], off
	global_load_dwordx4 v[96:99], v[148:149], off offset:1024
	v_lshl_add_u64 v[148:149], v[148:149], 0, s[18:19]
	global_load_dwordx4 v[100:103], v[148:149], off
	global_load_dwordx4 v[104:107], v[148:149], off offset:1024
	v_lshl_add_u64 v[148:149], v[148:149], 0, s[18:19]
	global_load_dwordx4 v[108:111], v[148:149], off
	global_load_dwordx4 v[112:115], v[148:149], off offset:1024
	v_lshl_add_u64 v[148:149], v[148:149], 0, s[18:19]
	global_load_dwordx4 v[116:119], v[148:149], off
	global_load_dwordx4 v[120:123], v[148:149], off offset:1024
	v_lshl_add_u64 v[148:149], v[148:149], 0, s[18:19]
	global_load_dwordx4 v[124:127], v[148:149], off
	global_load_dwordx4 v[128:131], v[148:149], off offset:1024
	v_lshl_add_u64 v[148:149], v[148:149], 0, s[18:19]
	global_load_dwordx4 v[132:135], v[148:149], off
	global_load_dwordx4 v[136:139], v[148:149], off offset:1024
	global_load_dwordx4 v[140:143], v[154:155], off
	global_load_dwordx4 v[144:147], v[154:155], off offset:1024
	s_waitcnt vmcnt(0)
; __device__ __forceinline__ void load_row(const Params& p, int r, int mode, int lane, f32x4 (&v)[8]) {
;     ...
;         const float* base = mode == 0 ? p.in[1] + (size_t)(r - TP) * DM : X + (size_t)r * DM;
;         const float alpha = mode == 1 ? 1.0f : 0.5f;
;         const float* P = (const float*)(p.ws + WS_PART) + (size_t)(r - TP) * DM;
; #pragma unroll
;         for (int j = 0; j < 8; ++j) {
;             f32x4 a = (f32x4){0.f, 0.f, 0.f, 0.f};
; #pragma unroll
;             for (int q = 0; q < 8; ++q) a += ((const f32x4*)(P + (size_t)q * 512 * DM))[j * 64 + lane];
;             v[j] = ((const f32x4*)base)[j * 64 + lane] + alpha * a;
;             if (mode < 2) ((f32x4*)(X + (size_t)r * DM))[j * 64 + lane] = v[j];
	v_pk_add_f32 v[78:79], v[78:79], 0 op_sel_hi:[1,0]
	v_pk_add_f32 v[76:77], v[76:77], 0 op_sel_hi:[1,0]
	v_pk_add_f32 v[78:79], v[78:79], v[86:87]
	v_pk_add_f32 v[76:77], v[76:77], v[84:85]
	v_pk_add_f32 v[78:79], v[78:79], v[94:95]
	v_pk_add_f32 v[76:77], v[76:77], v[92:93]
	v_pk_add_f32 v[78:79], v[78:79], v[102:103]
	v_pk_add_f32 v[76:77], v[76:77], v[100:101]
	v_pk_add_f32 v[78:79], v[78:79], v[110:111]
	v_pk_add_f32 v[76:77], v[76:77], v[108:109]
	v_pk_add_f32 v[78:79], v[78:79], v[118:119]
	v_pk_add_f32 v[76:77], v[76:77], v[116:117]
	v_pk_add_f32 v[78:79], v[78:79], v[126:127]
	v_pk_add_f32 v[76:77], v[76:77], v[124:125]
	v_pk_add_f32 v[78:79], v[78:79], v[134:135]
	v_pk_add_f32 v[76:77], v[76:77], v[132:133]
	v_pk_fma_f32 v[20:21], v[78:79], 0.5, v[142:143] op_sel_hi:[1,0,1]
	v_pk_fma_f32 v[18:19], v[76:77], 0.5, v[140:141] op_sel_hi:[1,0,1]
	global_store_dwordx4 v[158:159], v[18:21], off
	v_pk_add_f32 v[82:83], v[82:83], 0 op_sel_hi:[1,0]
	v_pk_add_f32 v[80:81], v[80:81], 0 op_sel_hi:[1,0]
	v_pk_add_f32 v[82:83], v[82:83], v[90:91]
	v_pk_add_f32 v[80:81], v[80:81], v[88:89]
	v_pk_add_f32 v[82:83], v[82:83], v[98:99]
	v_pk_add_f32 v[80:81], v[80:81], v[96:97]
	v_pk_add_f32 v[82:83], v[82:83], v[106:107]
	v_pk_add_f32 v[80:81], v[80:81], v[104:105]
	v_pk_add_f32 v[82:83], v[82:83], v[114:115]
	v_pk_add_f32 v[80:81], v[80:81], v[112:113]
	v_pk_add_f32 v[82:83], v[82:83], v[122:123]
	v_pk_add_f32 v[80:81], v[80:81], v[120:121]
	v_pk_add_f32 v[82:83], v[82:83], v[130:131]
	v_pk_add_f32 v[80:81], v[80:81], v[128:129]
	v_pk_add_f32 v[82:83], v[82:83], v[138:139]
	v_pk_add_f32 v[80:81], v[80:81], v[136:137]
	v_pk_fma_f32 v[24:25], v[82:83], 0.5, v[146:147] op_sel_hi:[1,0,1]
	v_pk_fma_f32 v[22:23], v[80:81], 0.5, v[144:145] op_sel_hi:[1,0,1]
	global_store_dwordx4 v[158:159], v[22:25], off offset:1024
	v_lshl_add_u64 v[148:149], v[152:153], 0, s[20:21]
	v_lshl_add_u64 v[154:155], v[150:151], 0, s[20:21]
	v_lshl_add_u64 v[158:159], v[156:157], 0, s[20:21]
	global_load_dwordx4 v[76:79], v[148:149], off offset:2048
	global_load_dwordx4 v[80:83], v[148:149], off offset:3072
	v_lshl_add_u64 v[148:149], v[148:149], 0, s[18:19]
	global_load_dwordx4 v[84:87], v[148:149], off offset:2048
	global_load_dwordx4 v[88:91], v[148:149], off offset:3072
	v_lshl_add_u64 v[148:149], v[148:149], 0, s[18:19]
	global_load_dwordx4 v[92:95], v[148:149], off offset:2048
	global_load_dwordx4 v[96:99], v[148:149], off offset:3072
	v_lshl_add_u64 v[148:149], v[148:149], 0, s[18:19]
	global_load_dwordx4 v[100:103], v[148:149], off offset:2048
	global_load_dwordx4 v[104:107], v[148:149], off offset:3072
	v_lshl_add_u64 v[148:149], v[148:149], 0, s[18:19]
	global_load_dwordx4 v[108:111], v[148:149], off offset:2048
	global_load_dwordx4 v[112:115], v[148:149], off offset:3072
	v_lshl_add_u64 v[148:149], v[148:149], 0, s[18:19]
	global_load_dwordx4 v[116:119], v[148:149], off offset:2048
	global_load_dwordx4 v[120:123], v[148:149], off offset:3072
	v_lshl_add_u64 v[148:149], v[148:149], 0, s[18:19]
	global_load_dwordx4 v[124:127], v[148:149], off offset:2048
	global_load_dwordx4 v[128:131], v[148:149], off offset:3072
	v_lshl_add_u64 v[148:149], v[148:149], 0, s[18:19]
	global_load_dwordx4 v[132:135], v[148:149], off offset:2048
	global_load_dwordx4 v[136:139], v[148:149], off offset:3072
	global_load_dwordx4 v[140:143], v[154:155], off offset:2048
	global_load_dwordx4 v[144:147], v[154:155], off offset:3072
	s_waitcnt vmcnt(0)
	v_pk_add_f32 v[78:79], v[78:79], 0 op_sel_hi:[1,0]
	v_pk_add_f32 v[76:77], v[76:77], 0 op_sel_hi:[1,0]
	v_pk_add_f32 v[78:79], v[78:79], v[86:87]
	v_pk_add_f32 v[76:77], v[76:77], v[84:85]
	v_pk_add_f32 v[78:79], v[78:79], v[94:95]
	v_pk_add_f32 v[76:77], v[76:77], v[92:93]
	v_pk_add_f32 v[78:79], v[78:79], v[102:103]
	v_pk_add_f32 v[76:77], v[76:77], v[100:101]
	v_pk_add_f32 v[78:79], v[78:79], v[110:111]
	v_pk_add_f32 v[76:77], v[76:77], v[108:109]
	v_pk_add_f32 v[78:79], v[78:79], v[118:119]
	v_pk_add_f32 v[76:77], v[76:77], v[116:117]
	v_pk_add_f32 v[78:79], v[78:79], v[126:127]
	v_pk_add_f32 v[76:77], v[76:77], v[124:125]
	v_pk_add_f32 v[78:79], v[78:79], v[134:135]
	v_pk_add_f32 v[76:77], v[76:77], v[132:133]
	v_pk_fma_f32 v[28:29], v[78:79], 0.5, v[142:143] op_sel_hi:[1,0,1]
	v_pk_fma_f32 v[26:27], v[76:77], 0.5, v[140:141] op_sel_hi:[1,0,1]
	global_store_dwordx4 v[158:159], v[26:29], off offset:2048
	v_pk_add_f32 v[82:83], v[82:83], 0 op_sel_hi:[1,0]
	v_pk_add_f32 v[80:81], v[80:81], 0 op_sel_hi:[1,0]
	v_pk_add_f32 v[82:83], v[82:83], v[90:91]
	v_pk_add_f32 v[80:81], v[80:81], v[88:89]
	v_pk_add_f32 v[82:83], v[82:83], v[98:99]
	v_pk_add_f32 v[80:81], v[80:81], v[96:97]
	v_pk_add_f32 v[82:83], v[82:83], v[106:107]
	v_pk_add_f32 v[80:81], v[80:81], v[104:105]
	v_pk_add_f32 v[82:83], v[82:83], v[114:115]
	v_pk_add_f32 v[80:81], v[80:81], v[112:113]
	v_pk_add_f32 v[82:83], v[82:83], v[122:123]
	v_pk_add_f32 v[80:81], v[80:81], v[120:121]
	v_pk_add_f32 v[82:83], v[82:83], v[130:131]
	v_pk_add_f32 v[80:81], v[80:81], v[128:129]
	v_pk_add_f32 v[82:83], v[82:83], v[138:139]
	v_pk_add_f32 v[80:81], v[80:81], v[136:137]
	v_pk_fma_f32 v[32:33], v[82:83], 0.5, v[146:147] op_sel_hi:[1,0,1]
	v_pk_fma_f32 v[30:31], v[80:81], 0.5, v[144:145] op_sel_hi:[1,0,1]
	global_store_dwordx4 v[158:159], v[30:33], off offset:3072
	v_mov_b64_e32 v[60:61], v[0:1]
